# combo1 + 64-byte alignment of GEMM main loops and attention steady loops
# baseline (speedup 1.0000x reference)
;     __device__ __forceinline__ bool next(int i, Unit& u) const { const int L = i * G + c; if (L >= nM * nN * ng) return false; const int per = nM * nN, r = L % per; u.g = L / per; u.pn = r / nM; u.pm = r % nM; return true; }
; template <class Epi, class Sched, bool ALIGN_EPI = false, bool SP2 = false>
; __device__ __forceinline__ void gemm_phase(PG8_LAS unsigned char* lds, const Gemm g, const Sched& S, const Epi& E) {
;     ...
;         const bool has_next = S.next(ui + 1, nxt);
;         const char* nA = has_next ? (const char*)g.A + (size_t)nxt.g * g.gsA * 2 + (size_t)nxt.pm * tstepA : cA; const char* nB = has_next ? (const char*)g.Bt + (size_t)nxt.g * g.gsB * 2 + (size_t)nxt.pn * tstepB : cB;
;     ...
; #pragma unroll
;         for (int a = 0; a < 2; ++a)
; #pragma unroll
;             for (int b = 0; b < 2; ++b)
; #pragma unroll
;                 for (int m = 0; m < 4; ++m)
; #pragma unroll
;                     for (int n = 0; n < 2; ++n) acc[a][b][m][n] = (f32x4){0.f, 0.f, 0.f, 0.f};
.LBB0_196:
	s_ashr_i32 s21, s20, 31
	s_lshl_b64 s[22:23], s[20:21], 19
	s_add_u32 s22, s3, s22
	s_addc_u32 s23, s34, s23
	s_and_b64 s[24:25], s[6:7], exec
	s_cselect_b32 s1, s23, s27
	s_cselect_b32 s2, s22, s26
	s_ashr_i32 s19, s18, 31
	s_lshl_b64 s[24:25], s[18:19], 19
	s_add_u32 s24, s35, s24
	s_addc_u32 s25, s36, s25
	s_and_b64 s[30:31], s[6:7], exec
	s_cselect_b32 s5, s25, s29
	s_cselect_b32 s19, s24, s28
	s_add_u32 s26, s26, 0x40080
	s_addc_u32 s27, s27, 0
	s_add_u32 s21, s28, 0x100
	v_mov_b64_e32 v[2:3], 0
	v_mov_b64_e32 v[4:5], 0
	v_mov_b64_e32 v[6:7], 0
	v_mov_b64_e32 v[8:9], 0
	v_mov_b64_e32 v[10:11], 0
	v_mov_b64_e32 v[12:13], 0
	v_mov_b64_e32 v[14:15], 0
	v_mov_b64_e32 v[16:17], 0
	v_mov_b64_e32 v[18:19], 0
	v_mov_b64_e32 v[20:21], 0
	v_mov_b64_e32 v[22:23], 0
	v_mov_b64_e32 v[24:25], 0
	v_mov_b64_e32 v[26:27], 0
	v_mov_b64_e32 v[28:29], 0
	v_mov_b64_e32 v[30:31], 0
	v_mov_b64_e32 v[32:33], 0
	v_mov_b64_e32 v[34:35], 0
	v_mov_b64_e32 v[36:37], 0
	v_mov_b64_e32 v[38:39], 0
	v_mov_b64_e32 v[40:41], 0
	v_mov_b64_e32 v[42:43], 0
	v_mov_b64_e32 v[44:45], 0
	v_mov_b64_e32 v[46:47], 0
	v_mov_b64_e32 v[48:49], 0
	v_mov_b64_e32 v[50:51], 0
	v_mov_b64_e32 v[52:53], 0
	v_mov_b64_e32 v[54:55], 0
	v_mov_b64_e32 v[56:57], 0
	v_mov_b64_e32 v[58:59], 0
	v_mov_b64_e32 v[60:61], 0
	v_mov_b64_e32 v[62:63], 0
	v_mov_b64_e32 v[64:65], 0
	v_mov_b64_e32 v[66:67], 0
	v_mov_b64_e32 v[68:69], 0
	v_mov_b64_e32 v[70:71], 0
	v_mov_b64_e32 v[72:73], 0
	v_mov_b64_e32 v[74:75], 0
	v_mov_b64_e32 v[76:77], 0
	v_mov_b64_e32 v[78:79], 0
	v_mov_b64_e32 v[80:81], 0
	v_mov_b64_e32 v[82:83], 0
	v_mov_b64_e32 v[84:85], 0
	v_mov_b64_e32 v[86:87], 0
	v_mov_b64_e32 v[88:89], 0
	v_mov_b64_e32 v[90:91], 0
	v_mov_b64_e32 v[92:93], 0
	v_mov_b64_e32 v[94:95], 0
	v_mov_b64_e32 v[96:97], 0
	v_mov_b64_e32 v[98:99], 0
	v_mov_b64_e32 v[100:101], 0
	v_mov_b64_e32 v[102:103], 0
	v_mov_b64_e32 v[104:105], 0
	v_mov_b64_e32 v[106:107], 0
	v_mov_b64_e32 v[108:109], 0
	v_mov_b64_e32 v[110:111], 0
	v_mov_b64_e32 v[112:113], 0
	v_mov_b64_e32 v[114:115], 0
	v_mov_b64_e32 v[116:117], 0
	v_mov_b64_e32 v[118:119], 0
	v_mov_b64_e32 v[120:121], 0
	v_mov_b64_e32 v[122:123], 0
	v_mov_b64_e32 v[124:125], 0
	v_mov_b64_e32 v[126:127], 0
	v_mov_b64_e32 v[128:129], 0
	s_addc_u32 s33, s29, 0
	s_mov_b32 s60, -2
	s_waitcnt lgkmcnt(0)
	.p2alignl 6, 3212836864

;     __device__ __forceinline__ bool next(int i, Unit& u) const { const int L = i * G + c; if (L >= nM * nN * ng) return false; const int per = nM * nN, r = L % per; u.g = L / per; u.pn = r / nM; u.pm = r % nM; return true; }
; template <class Epi, class Sched, bool ALIGN_EPI = false, bool SP2 = false>
; __device__ __forceinline__ void gemm_phase(PG8_LAS unsigned char* lds, const Gemm g, const Sched& S, const Epi& E) {
;     ...
;         const bool has_next = S.next(ui + 1, nxt);
;         const char* nA = has_next ? (const char*)g.A + (size_t)nxt.g * g.gsA * 2 + (size_t)nxt.pm * tstepA : cA; const char* nB = has_next ? (const char*)g.Bt + (size_t)nxt.g * g.gsB * 2 + (size_t)nxt.pn * tstepB : cB;
;     ...
; #pragma unroll
;         for (int a = 0; a < 2; ++a)
; #pragma unroll
;             for (int b = 0; b < 2; ++b)
; #pragma unroll
;                 for (int m = 0; m < 4; ++m)
; #pragma unroll
;                     for (int n = 0; n < 2; ++n) acc[a][b][m][n] = (f32x4){0.f, 0.f, 0.f, 0.f};
.LBB0_279:
	s_lshl_b64 s[34:35], s[28:29], 18
	s_add_u32 s34, s33, s34
	s_addc_u32 s35, s44, s35
	s_and_b64 s[40:41], s[40:41], exec
	s_cselect_b32 s9, s35, s39
	s_cselect_b32 s29, s34, s38
	s_add_u32 s66, s38, 0x100
	v_mov_b32_e32 v2, 0
	s_addc_u32 s67, s39, 0
	s_mov_b32 s68, -2
	v_mov_b32_e32 v3, v2
	v_mov_b32_e32 v4, v2
	v_mov_b32_e32 v5, v2
	v_mov_b32_e32 v6, v2
	v_mov_b32_e32 v7, v2
	v_mov_b32_e32 v8, v2
	v_mov_b32_e32 v9, v2
	v_mov_b32_e32 v10, v2
	v_mov_b32_e32 v11, v2
	v_mov_b32_e32 v12, v2
	v_mov_b32_e32 v13, v2
	v_mov_b32_e32 v14, v2
	v_mov_b32_e32 v15, v2
	v_mov_b32_e32 v16, v2
	v_mov_b32_e32 v17, v2
	v_mov_b32_e32 v18, v2
	v_mov_b32_e32 v19, v2
	v_mov_b32_e32 v20, v2
	v_mov_b32_e32 v21, v2
	v_mov_b32_e32 v22, v2
	v_mov_b32_e32 v23, v2
	v_mov_b32_e32 v24, v2
	v_mov_b32_e32 v25, v2
	v_mov_b32_e32 v26, v2
	v_mov_b32_e32 v27, v2
	v_mov_b32_e32 v28, v2
	v_mov_b32_e32 v29, v2
	v_mov_b32_e32 v30, v2
	v_mov_b32_e32 v31, v2
	v_mov_b32_e32 v32, v2
	v_mov_b32_e32 v33, v2
	v_mov_b32_e32 v34, v2
	v_mov_b32_e32 v35, v2
	v_mov_b32_e32 v36, v2
	v_mov_b32_e32 v37, v2
	v_mov_b32_e32 v38, v2
	v_mov_b32_e32 v39, v2
	v_mov_b32_e32 v40, v2
	v_mov_b32_e32 v41, v2
	v_mov_b32_e32 v42, v2
	v_mov_b32_e32 v43, v2
	v_mov_b32_e32 v44, v2
	v_mov_b32_e32 v45, v2
	v_mov_b32_e32 v46, v2
	v_mov_b32_e32 v47, v2
	v_mov_b32_e32 v48, v2
	v_mov_b32_e32 v49, v2
	v_mov_b32_e32 v50, v2
	s_waitcnt lgkmcnt(0)
	v_mov_b32_e32 v51, v2
	v_mov_b32_e32 v52, v2
	v_mov_b32_e32 v53, v2
	v_mov_b32_e32 v54, v2
	v_mov_b32_e32 v55, v2
	v_mov_b32_e32 v56, v2
	v_mov_b32_e32 v57, v2
	v_mov_b32_e32 v58, v2
	v_mov_b32_e32 v59, v2
	v_mov_b32_e32 v60, v2
	v_mov_b32_e32 v61, v2
	v_mov_b32_e32 v62, v2
	v_mov_b32_e32 v63, v2
	v_mov_b32_e32 v64, v2
	v_mov_b32_e32 v65, v2
	.p2alignl 6, 3212836864

; template <class Epi, class Sched, bool ALIGN_EPI = false, bool SP2 = false>
; __device__ __forceinline__ void gemm_phase(PG8_LAS unsigned char* lds, const Gemm g, const Sched& S, const Epi& E) {
;     ...
; #pragma unroll
;         for (int a = 0; a < 2; ++a)
; #pragma unroll
;             for (int b = 0; b < 2; ++b)
; #pragma unroll
;                 for (int m = 0; m < 4; ++m)
; #pragma unroll
;                     for (int n = 0; n < 2; ++n) acc[a][b][m][n] = (f32x4){0.f, 0.f, 0.f, 0.f};
.LBB0_429:
	s_add_u32 s2, s42, 0x100
	v_mov_b64_e32 v[2:3], 0
	v_mov_b64_e32 v[4:5], 0
	v_mov_b64_e32 v[6:7], 0
	v_mov_b64_e32 v[8:9], 0
	v_mov_b64_e32 v[10:11], 0
	v_mov_b64_e32 v[12:13], 0
	v_mov_b64_e32 v[14:15], 0
	v_mov_b64_e32 v[16:17], 0
	v_mov_b64_e32 v[18:19], 0
	v_mov_b64_e32 v[20:21], 0
	v_mov_b64_e32 v[22:23], 0
	v_mov_b64_e32 v[24:25], 0
	v_mov_b64_e32 v[26:27], 0
	v_mov_b64_e32 v[28:29], 0
	v_mov_b64_e32 v[30:31], 0
	v_mov_b64_e32 v[32:33], 0
	v_mov_b64_e32 v[34:35], 0
	v_mov_b64_e32 v[36:37], 0
	v_mov_b64_e32 v[38:39], 0
	v_mov_b64_e32 v[40:41], 0
	v_mov_b64_e32 v[42:43], 0
	v_mov_b64_e32 v[44:45], 0
	v_mov_b64_e32 v[46:47], 0
	v_mov_b64_e32 v[48:49], 0
	v_mov_b64_e32 v[50:51], 0
	v_mov_b64_e32 v[52:53], 0
	v_mov_b64_e32 v[54:55], 0
	v_mov_b64_e32 v[56:57], 0
	v_mov_b64_e32 v[58:59], 0
	v_mov_b64_e32 v[60:61], 0
	v_mov_b64_e32 v[70:71], 0
	v_mov_b64_e32 v[72:73], 0
	v_mov_b64_e32 v[74:75], 0
	v_mov_b64_e32 v[76:77], 0
	v_mov_b64_e32 v[78:79], 0
	v_mov_b64_e32 v[80:81], 0
	v_mov_b64_e32 v[82:83], 0
	v_mov_b64_e32 v[84:85], 0
	v_mov_b64_e32 v[86:87], 0
	v_mov_b64_e32 v[88:89], 0
	v_mov_b64_e32 v[90:91], 0
	v_mov_b64_e32 v[92:93], 0
	v_mov_b64_e32 v[94:95], 0
	v_mov_b64_e32 v[96:97], 0
	v_mov_b64_e32 v[98:99], 0
	v_mov_b64_e32 v[100:101], 0
	v_mov_b64_e32 v[102:103], 0
	v_mov_b64_e32 v[104:105], 0
	v_mov_b64_e32 v[106:107], 0
	v_mov_b64_e32 v[108:109], 0
	v_mov_b64_e32 v[110:111], 0
	v_mov_b64_e32 v[112:113], 0
	v_mov_b64_e32 v[114:115], 0
	v_mov_b64_e32 v[116:117], 0
	v_mov_b64_e32 v[118:119], 0
	v_mov_b64_e32 v[120:121], 0
	v_mov_b64_e32 v[122:123], 0
	v_mov_b64_e32 v[124:125], 0
	v_mov_b64_e32 v[126:127], 0
	v_mov_b64_e32 v[128:129], 0
	v_mov_b64_e32 v[130:131], 0
	v_mov_b64_e32 v[132:133], 0
	v_mov_b64_e32 v[134:135], 0
	v_mov_b64_e32 v[136:137], 0
	s_addc_u32 s5, s43, 0
	s_mov_b32 s33, -2
	.p2alignl 6, 3212836864

;     __device__ __forceinline__ bool next(int i, Unit& u) const { const int L = i * G + c; if (L >= nM * nN * ng) return false; const int per = nM * nN, r = L % per; u.g = L / per; u.pn = r / nM; u.pm = r % nM; return true; }
; template <class Epi, class Sched, bool ALIGN_EPI = false, bool SP2 = false>
; __device__ __forceinline__ void gemm_phase(PG8_LAS unsigned char* lds, const Gemm g, const Sched& S, const Epi& E) {
;     ...
;         const bool has_next = S.next(ui + 1, nxt);
;         const char* nA = has_next ? (const char*)g.A + (size_t)nxt.g * g.gsA * 2 + (size_t)nxt.pm * tstepA : cA; const char* nB = has_next ? (const char*)g.Bt + (size_t)nxt.g * g.gsB * 2 + (size_t)nxt.pn * tstepB : cB;
;     ...
; #pragma unroll
;         for (int a = 0; a < 2; ++a)
; #pragma unroll
;             for (int b = 0; b < 2; ++b)
; #pragma unroll
;                 for (int m = 0; m < 4; ++m)
; #pragma unroll
;                     for (int n = 0; n < 2; ++n) acc[a][b][m][n] = (f32x4){0.f, 0.f, 0.f, 0.f};
.LBB0_522:
	s_ashr_i32 s19, s18, 31
	s_lshl_b64 s[20:21], s[18:19], 18
	s_add_u32 s20, s8, s20
	s_addc_u32 s21, s9, s21
	s_and_b64 s[22:23], s[6:7], exec
	s_cselect_b32 s19, s21, s27
	s_cselect_b32 s44, s20, s26
	s_ashr_i32 s17, s16, 31
	s_lshl_b64 s[22:23], s[16:17], 18
	s_add_u32 s22, s33, s22
	s_addc_u32 s23, s34, s23
	s_and_b64 s[30:31], s[6:7], exec
	s_cselect_b32 s17, s23, s29
	s_cselect_b32 s45, s22, s28
	s_add_u32 s26, s26, 0x20080
	s_addc_u32 s27, s27, 0
	s_add_u32 s46, s28, 0x100
	v_mov_b64_e32 v[2:3], 0
	v_mov_b64_e32 v[4:5], 0
	v_mov_b64_e32 v[6:7], 0
	v_mov_b64_e32 v[8:9], 0
	v_mov_b64_e32 v[10:11], 0
	v_mov_b64_e32 v[12:13], 0
	v_mov_b64_e32 v[14:15], 0
	v_mov_b64_e32 v[16:17], 0
	v_mov_b64_e32 v[18:19], 0
	v_mov_b64_e32 v[20:21], 0
	v_mov_b64_e32 v[22:23], 0
	v_mov_b64_e32 v[24:25], 0
	v_mov_b64_e32 v[26:27], 0
	v_mov_b64_e32 v[28:29], 0
	v_mov_b64_e32 v[30:31], 0
	v_mov_b64_e32 v[32:33], 0
	v_mov_b64_e32 v[34:35], 0
	v_mov_b64_e32 v[36:37], 0
	v_mov_b64_e32 v[38:39], 0
	v_mov_b64_e32 v[40:41], 0
	v_mov_b64_e32 v[42:43], 0
	v_mov_b64_e32 v[44:45], 0
	v_mov_b64_e32 v[46:47], 0
	v_mov_b64_e32 v[48:49], 0
	v_mov_b64_e32 v[50:51], 0
	v_mov_b64_e32 v[52:53], 0
	v_mov_b64_e32 v[54:55], 0
	v_mov_b64_e32 v[56:57], 0
	v_mov_b64_e32 v[58:59], 0
	v_mov_b64_e32 v[60:61], 0
	v_mov_b64_e32 v[62:63], 0
	v_mov_b64_e32 v[64:65], 0
	v_mov_b64_e32 v[66:67], 0
	v_mov_b64_e32 v[68:69], 0
	v_mov_b64_e32 v[70:71], 0
	v_mov_b64_e32 v[72:73], 0
	v_mov_b64_e32 v[74:75], 0
	v_mov_b64_e32 v[76:77], 0
	v_mov_b64_e32 v[78:79], 0
	v_mov_b64_e32 v[80:81], 0
	v_mov_b64_e32 v[82:83], 0
	v_mov_b64_e32 v[84:85], 0
	v_mov_b64_e32 v[86:87], 0
	v_mov_b64_e32 v[88:89], 0
	v_mov_b64_e32 v[90:91], 0
	v_mov_b64_e32 v[92:93], 0
	v_mov_b64_e32 v[94:95], 0
	v_mov_b64_e32 v[96:97], 0
	v_mov_b64_e32 v[98:99], 0
	v_mov_b64_e32 v[100:101], 0
	v_mov_b64_e32 v[102:103], 0
	v_mov_b64_e32 v[104:105], 0
	v_mov_b64_e32 v[106:107], 0
	v_mov_b64_e32 v[108:109], 0
	v_mov_b64_e32 v[110:111], 0
	v_mov_b64_e32 v[112:113], 0
	v_mov_b64_e32 v[114:115], 0
	v_mov_b64_e32 v[116:117], 0
	v_mov_b64_e32 v[118:119], 0
	v_mov_b64_e32 v[120:121], 0
	v_mov_b64_e32 v[122:123], 0
	v_mov_b64_e32 v[124:125], 0
	v_mov_b64_e32 v[126:127], 0
	v_mov_b64_e32 v[128:129], 0
	s_addc_u32 s47, s29, 0
	s_mov_b32 s48, -2
	s_waitcnt lgkmcnt(0)
	.p2alignl 6, 3212836864

;     __device__ __forceinline__ bool next(int i, Unit& u) const { const int L = i * G + c; if (L >= nM * nN * ng) return false; const int per = nM * nN, r = L % per; u.g = L / per; u.pn = r / nM; u.pm = r % nM; return true; }
; template <class Epi, class Sched, bool ALIGN_EPI = false, bool SP2 = false>
; __device__ __forceinline__ void gemm_phase(PG8_LAS unsigned char* lds, const Gemm g, const Sched& S, const Epi& E) {
;     ...
;         const bool has_next = S.next(ui + 1, nxt);
;         const char* nA = has_next ? (const char*)g.A + (size_t)nxt.g * g.gsA * 2 + (size_t)nxt.pm * tstepA : cA; const char* nB = has_next ? (const char*)g.Bt + (size_t)nxt.g * g.gsB * 2 + (size_t)nxt.pn * tstepB : cB;
;     ...
; #pragma unroll
;         for (int a = 0; a < 2; ++a)
; #pragma unroll
;             for (int b = 0; b < 2; ++b)
; #pragma unroll
;                 for (int m = 0; m < 4; ++m)
; #pragma unroll
;                     for (int n = 0; n < 2; ++n) acc[a][b][m][n] = (f32x4){0.f, 0.f, 0.f, 0.f};
.LBB0_604:
	s_ashr_i32 s25, s24, 31
	s_lshl_b64 s[26:27], s[24:25], 19
	s_add_u32 s26, s0, s26
	s_addc_u32 s27, s1, s27
	s_and_b64 s[28:29], s[8:9], exec
	s_cselect_b32 s25, s27, s35
	s_cselect_b32 s31, s26, s34
	s_ashr_i32 s23, s22, 31
	s_lshl_b64 s[28:29], s[22:23], 19
	s_add_u32 s28, s2, s28
	s_addc_u32 s29, s3, s29
	s_and_b64 s[38:39], s[8:9], exec
	s_cselect_b32 s23, s29, s37
	s_cselect_b32 s53, s28, s36
	s_add_u32 s34, s34, 0x40080
	s_addc_u32 s35, s35, 0
	s_add_u32 s54, s36, 0x100
	v_mov_b64_e32 v[2:3], 0
	v_mov_b64_e32 v[4:5], 0
	v_mov_b64_e32 v[6:7], 0
	v_mov_b64_e32 v[8:9], 0
	v_mov_b64_e32 v[10:11], 0
	v_mov_b64_e32 v[12:13], 0
	v_mov_b64_e32 v[14:15], 0
	v_mov_b64_e32 v[16:17], 0
	v_mov_b64_e32 v[18:19], 0
	v_mov_b64_e32 v[20:21], 0
	v_mov_b64_e32 v[22:23], 0
	v_mov_b64_e32 v[24:25], 0
	v_mov_b64_e32 v[26:27], 0
	v_mov_b64_e32 v[28:29], 0
	v_mov_b64_e32 v[30:31], 0
	v_mov_b64_e32 v[32:33], 0
	v_mov_b64_e32 v[34:35], 0
	v_mov_b64_e32 v[36:37], 0
	v_mov_b64_e32 v[38:39], 0
	v_mov_b64_e32 v[40:41], 0
	v_mov_b64_e32 v[42:43], 0
	v_mov_b64_e32 v[44:45], 0
	v_mov_b64_e32 v[46:47], 0
	v_mov_b64_e32 v[48:49], 0
	v_mov_b64_e32 v[50:51], 0
	v_mov_b64_e32 v[52:53], 0
	v_mov_b64_e32 v[54:55], 0
	v_mov_b64_e32 v[56:57], 0
	v_mov_b64_e32 v[58:59], 0
	v_mov_b64_e32 v[60:61], 0
	v_mov_b64_e32 v[62:63], 0
	v_mov_b64_e32 v[64:65], 0
	v_mov_b64_e32 v[66:67], 0
	v_mov_b64_e32 v[68:69], 0
	v_mov_b64_e32 v[70:71], 0
	v_mov_b64_e32 v[72:73], 0
	v_mov_b64_e32 v[74:75], 0
	v_mov_b64_e32 v[76:77], 0
	v_mov_b64_e32 v[78:79], 0
	v_mov_b64_e32 v[80:81], 0
	v_mov_b64_e32 v[82:83], 0
	v_mov_b64_e32 v[84:85], 0
	v_mov_b64_e32 v[86:87], 0
	v_mov_b64_e32 v[88:89], 0
	v_mov_b64_e32 v[90:91], 0
	v_mov_b64_e32 v[92:93], 0
	v_mov_b64_e32 v[94:95], 0
	v_mov_b64_e32 v[96:97], 0
	v_mov_b64_e32 v[98:99], 0
	v_mov_b64_e32 v[100:101], 0
	v_mov_b64_e32 v[102:103], 0
	v_mov_b64_e32 v[104:105], 0
	v_mov_b64_e32 v[106:107], 0
	v_mov_b64_e32 v[108:109], 0
	v_mov_b64_e32 v[110:111], 0
	v_mov_b64_e32 v[112:113], 0
	v_mov_b64_e32 v[114:115], 0
	v_mov_b64_e32 v[116:117], 0
	v_mov_b64_e32 v[118:119], 0
	v_mov_b64_e32 v[120:121], 0
	v_mov_b64_e32 v[122:123], 0
	v_mov_b64_e32 v[124:125], 0
	v_mov_b64_e32 v[126:127], 0
	v_mov_b64_e32 v[128:129], 0
	s_addc_u32 s55, s37, 0
	s_mov_b32 s56, -2
	s_waitcnt lgkmcnt(0)
	s_waitcnt lgkmcnt(0)
	.p2alignl 6, 3212836864

;     __device__ __forceinline__ bool next(int i, Unit& u) const { const int L = i * G + c; if (L >= nM * nN * ng) return false; const int per = nM * nN, r = L % per; u.g = L / per; u.pn = r / nM; u.pm = r % nM; return true; }
; template <class Epi, class Sched, bool ALIGN_EPI = false, bool SP2 = false>
; __device__ __forceinline__ void gemm_phase(PG8_LAS unsigned char* lds, const Gemm g, const Sched& S, const Epi& E) {
;     ...
;         const bool has_next = S.next(ui + 1, nxt);
;         const char* nA = has_next ? (const char*)g.A + (size_t)nxt.g * g.gsA * 2 + (size_t)nxt.pm * tstepA : cA; const char* nB = has_next ? (const char*)g.Bt + (size_t)nxt.g * g.gsB * 2 + (size_t)nxt.pn * tstepB : cB;
;     ...
; #pragma unroll
;         for (int a = 0; a < 2; ++a)
; #pragma unroll
;             for (int b = 0; b < 2; ++b)
; #pragma unroll
;                 for (int m = 0; m < 4; ++m)
; #pragma unroll
;                     for (int n = 0; n < 2; ++n) acc[a][b][m][n] = (f32x4){0.f, 0.f, 0.f, 0.f};
.LBB0_690:
	s_ashr_i32 s17, s16, 31
	s_lshl_b64 s[18:19], s[16:17], 19
	s_add_u32 s18, s0, s18
	s_addc_u32 s19, s1, s19
	s_and_b64 s[20:21], s[6:7], exec
	s_cselect_b32 s17, s19, s25
	s_cselect_b32 s46, s18, s24
	s_ashr_i32 s15, s14, 31
	s_lshl_b64 s[20:21], s[14:15], 19
	s_add_u32 s20, s2, s20
	s_addc_u32 s21, s3, s21
	s_and_b64 s[28:29], s[6:7], exec
	s_cselect_b32 s15, s21, s27
	s_cselect_b32 s47, s20, s26
	s_add_u32 s24, s24, 0x40080
	s_addc_u32 s25, s25, 0
	s_add_u32 s48, s26, 0x100
	v_mov_b64_e32 v[2:3], 0
	v_mov_b64_e32 v[4:5], 0
	v_mov_b64_e32 v[6:7], 0
	v_mov_b64_e32 v[8:9], 0
	v_mov_b64_e32 v[10:11], 0
	v_mov_b64_e32 v[12:13], 0
	v_mov_b64_e32 v[14:15], 0
	v_mov_b64_e32 v[16:17], 0
	v_mov_b64_e32 v[18:19], 0
	v_mov_b64_e32 v[20:21], 0
	v_mov_b64_e32 v[22:23], 0
	v_mov_b64_e32 v[24:25], 0
	v_mov_b64_e32 v[26:27], 0
	v_mov_b64_e32 v[28:29], 0
	v_mov_b64_e32 v[30:31], 0
	v_mov_b64_e32 v[32:33], 0
	v_mov_b64_e32 v[34:35], 0
	v_mov_b64_e32 v[36:37], 0
	v_mov_b64_e32 v[38:39], 0
	v_mov_b64_e32 v[40:41], 0
	v_mov_b64_e32 v[42:43], 0
	v_mov_b64_e32 v[44:45], 0
	v_mov_b64_e32 v[46:47], 0
	v_mov_b64_e32 v[48:49], 0
	v_mov_b64_e32 v[50:51], 0
	v_mov_b64_e32 v[52:53], 0
	v_mov_b64_e32 v[54:55], 0
	v_mov_b64_e32 v[56:57], 0
	v_mov_b64_e32 v[58:59], 0
	v_mov_b64_e32 v[60:61], 0
	v_mov_b64_e32 v[62:63], 0
	v_mov_b64_e32 v[64:65], 0
	v_mov_b64_e32 v[66:67], 0
	v_mov_b64_e32 v[68:69], 0
	v_mov_b64_e32 v[70:71], 0
	v_mov_b64_e32 v[72:73], 0
	v_mov_b64_e32 v[74:75], 0
	v_mov_b64_e32 v[76:77], 0
	v_mov_b64_e32 v[78:79], 0
	v_mov_b64_e32 v[80:81], 0
	v_mov_b64_e32 v[82:83], 0
	v_mov_b64_e32 v[84:85], 0
	v_mov_b64_e32 v[86:87], 0
	v_mov_b64_e32 v[88:89], 0
	v_mov_b64_e32 v[90:91], 0
	v_mov_b64_e32 v[92:93], 0
	v_mov_b64_e32 v[94:95], 0
	v_mov_b64_e32 v[96:97], 0
	v_mov_b64_e32 v[98:99], 0
	v_mov_b64_e32 v[100:101], 0
	v_mov_b64_e32 v[102:103], 0
	v_mov_b64_e32 v[104:105], 0
	v_mov_b64_e32 v[106:107], 0
	v_mov_b64_e32 v[108:109], 0
	v_mov_b64_e32 v[110:111], 0
	v_mov_b64_e32 v[112:113], 0
	v_mov_b64_e32 v[114:115], 0
	v_mov_b64_e32 v[116:117], 0
	v_mov_b64_e32 v[118:119], 0
	v_mov_b64_e32 v[120:121], 0
	v_mov_b64_e32 v[122:123], 0
	v_mov_b64_e32 v[124:125], 0
	v_mov_b64_e32 v[126:127], 0
	v_mov_b64_e32 v[128:129], 0
	s_addc_u32 s49, s27, 0
	s_mov_b32 s50, -2
	.p2alignl 6, 3212836864

; template <class Epi, class Sched, bool ALIGN_EPI = false, bool SP2 = false>
; __device__ __forceinline__ void gemm_phase(PG8_LAS unsigned char* lds, const Gemm g, const Sched& S, const Epi& E) {
;     ...
; #pragma unroll
;         for (int a = 0; a < 2; ++a)
; #pragma unroll
;             for (int b = 0; b < 2; ++b)
; #pragma unroll
;                 for (int m = 0; m < 4; ++m)
; #pragma unroll
;                     for (int n = 0; n < 2; ++n) acc[a][b][m][n] = (f32x4){0.f, 0.f, 0.f, 0.f};
.LBB0_775:
	s_add_u32 s4, s28, 0x100
	v_mov_b64_e32 v[2:3], 0
	v_mov_b64_e32 v[4:5], 0
	v_mov_b64_e32 v[6:7], 0
	v_mov_b64_e32 v[8:9], 0
	v_mov_b64_e32 v[10:11], 0
	v_mov_b64_e32 v[12:13], 0
	v_mov_b64_e32 v[14:15], 0
	v_mov_b64_e32 v[16:17], 0
	v_mov_b64_e32 v[18:19], 0
	v_mov_b64_e32 v[20:21], 0
	v_mov_b64_e32 v[22:23], 0
	v_mov_b64_e32 v[24:25], 0
	v_mov_b64_e32 v[26:27], 0
	v_mov_b64_e32 v[28:29], 0
	v_mov_b64_e32 v[30:31], 0
	v_mov_b64_e32 v[32:33], 0
	v_mov_b64_e32 v[34:35], 0
	v_mov_b64_e32 v[36:37], 0
	v_mov_b64_e32 v[38:39], 0
	v_mov_b64_e32 v[40:41], 0
	v_mov_b64_e32 v[42:43], 0
	v_mov_b64_e32 v[44:45], 0
	v_mov_b64_e32 v[46:47], 0
	v_mov_b64_e32 v[48:49], 0
	v_mov_b64_e32 v[50:51], 0
	v_mov_b64_e32 v[52:53], 0
	v_mov_b64_e32 v[54:55], 0
	v_mov_b64_e32 v[56:57], 0
	v_mov_b64_e32 v[58:59], 0
	v_mov_b64_e32 v[60:61], 0
	v_mov_b64_e32 v[62:63], 0
	v_mov_b64_e32 v[64:65], 0
	v_mov_b64_e32 v[66:67], 0
	v_mov_b64_e32 v[68:69], 0
	v_mov_b64_e32 v[70:71], 0
	v_mov_b64_e32 v[72:73], 0
	v_mov_b64_e32 v[74:75], 0
	v_mov_b64_e32 v[76:77], 0
	v_mov_b64_e32 v[78:79], 0
	v_mov_b64_e32 v[80:81], 0
	v_mov_b64_e32 v[82:83], 0
	v_mov_b64_e32 v[84:85], 0
	v_mov_b64_e32 v[86:87], 0
	v_mov_b64_e32 v[88:89], 0
	v_mov_b64_e32 v[90:91], 0
	v_mov_b64_e32 v[92:93], 0
	v_mov_b64_e32 v[94:95], 0
	v_mov_b64_e32 v[96:97], 0
	v_mov_b64_e32 v[98:99], 0
	v_mov_b64_e32 v[100:101], 0
	v_mov_b64_e32 v[102:103], 0
	v_mov_b64_e32 v[104:105], 0
	v_mov_b64_e32 v[106:107], 0
	v_mov_b64_e32 v[108:109], 0
	v_mov_b64_e32 v[110:111], 0
	v_mov_b64_e32 v[112:113], 0
	v_mov_b64_e32 v[114:115], 0
	v_mov_b64_e32 v[116:117], 0
	v_mov_b64_e32 v[118:119], 0
	v_mov_b64_e32 v[120:121], 0
	v_mov_b64_e32 v[122:123], 0
	v_mov_b64_e32 v[124:125], 0
	v_mov_b64_e32 v[126:127], 0
	v_mov_b64_e32 v[128:129], 0
	s_addc_u32 s53, s29, 0
	s_mov_b32 s54, -2
	s_waitcnt lgkmcnt(0)
	.p2alignl 6, 3212836864

; template <class Epi, class Sched, bool ALIGN_EPI = false, bool SP2 = false>
; __device__ __forceinline__ void gemm_phase(PG8_LAS unsigned char* lds, const Gemm g, const Sched& S, const Epi& E) {
;     ...
;         for (int t = 0; t < nt; t += 2) {
;             const bool last = (t == nt - 2);
;     ...
; #pragma unroll
;         for (int a = 0; a < 2; ++a)
; #pragma unroll
;             for (int b = 0; b < 2; ++b)
; #pragma unroll
;                 for (int m = 0; m < 4; ++m)
; #pragma unroll
;                     for (int n = 0; n < 2; ++n) acc[a][b][m][n] = (f32x4){0.f, 0.f, 0.f, 0.f};
.LBB0_819:
	v_mov_b32_e32 v125, 0
	s_andn2_b64 vcc, exec, s[22:23]
	v_mov_b32_e32 v124, v125
	v_mov_b32_e32 v123, v125
	v_mov_b32_e32 v122, v125
	v_mov_b32_e32 v129, v125
	v_mov_b32_e32 v128, v125
	v_mov_b32_e32 v127, v125
	v_mov_b32_e32 v126, v125
	v_mov_b32_e32 v113, v125
	v_mov_b32_e32 v112, v125
	v_mov_b32_e32 v111, v125
	v_mov_b32_e32 v110, v125
	v_mov_b32_e32 v109, v125
	v_mov_b32_e32 v108, v125
	v_mov_b32_e32 v107, v125
	v_mov_b32_e32 v106, v125
	v_mov_b32_e32 v97, v125
	v_mov_b32_e32 v96, v125
	v_mov_b32_e32 v95, v125
	v_mov_b32_e32 v94, v125
	v_mov_b32_e32 v93, v125
	v_mov_b32_e32 v92, v125
	v_mov_b32_e32 v91, v125
	v_mov_b32_e32 v90, v125
	v_mov_b32_e32 v81, v125
	v_mov_b32_e32 v80, v125
	v_mov_b32_e32 v79, v125
	v_mov_b32_e32 v78, v125
	v_mov_b32_e32 v77, v125
	v_mov_b32_e32 v76, v125
	v_mov_b32_e32 v75, v125
	v_mov_b32_e32 v74, v125
	v_mov_b32_e32 v121, v125
	v_mov_b32_e32 v120, v125
	v_mov_b32_e32 v119, v125
	v_mov_b32_e32 v118, v125
	v_mov_b32_e32 v117, v125
	v_mov_b32_e32 v116, v125
	v_mov_b32_e32 v115, v125
	v_mov_b32_e32 v114, v125
	v_mov_b32_e32 v105, v125
	v_mov_b32_e32 v104, v125
	v_mov_b32_e32 v103, v125
	v_mov_b32_e32 v102, v125
	v_mov_b32_e32 v101, v125
	v_mov_b32_e32 v100, v125
	v_mov_b32_e32 v99, v125
	v_mov_b32_e32 v98, v125
	v_mov_b32_e32 v89, v125
	v_mov_b32_e32 v88, v125
	v_mov_b32_e32 v87, v125
	v_mov_b32_e32 v86, v125
	v_mov_b32_e32 v85, v125
	v_mov_b32_e32 v84, v125
	v_mov_b32_e32 v83, v125
	v_mov_b32_e32 v82, v125
	v_mov_b32_e32 v73, v125
	v_mov_b32_e32 v72, v125
	v_mov_b32_e32 v71, v125
	v_mov_b32_e32 v70, v125
	v_mov_b32_e32 v69, v125
	v_mov_b32_e32 v68, v125
	v_mov_b32_e32 v67, v125
	v_mov_b32_e32 v66, v125
	v_mov_b32_e32 v65, v125
	v_mov_b32_e32 v64, v125
	v_mov_b32_e32 v63, v125
	v_mov_b32_e32 v62, v125
	v_mov_b32_e32 v61, v125
	v_mov_b32_e32 v60, v125
	v_mov_b32_e32 v59, v125
	v_mov_b32_e32 v58, v125
	v_mov_b32_e32 v49, v125
	v_mov_b32_e32 v48, v125
	v_mov_b32_e32 v47, v125
	v_mov_b32_e32 v46, v125
	v_mov_b32_e32 v45, v125
	v_mov_b32_e32 v44, v125
	v_mov_b32_e32 v43, v125
	v_mov_b32_e32 v42, v125
	v_mov_b32_e32 v33, v125
	v_mov_b32_e32 v32, v125
	v_mov_b32_e32 v31, v125
	v_mov_b32_e32 v30, v125
	v_mov_b32_e32 v29, v125
	v_mov_b32_e32 v28, v125
	v_mov_b32_e32 v27, v125
	v_mov_b32_e32 v26, v125
	v_mov_b32_e32 v17, v125
	v_mov_b32_e32 v16, v125
	v_mov_b32_e32 v15, v125
	v_mov_b32_e32 v14, v125
	v_mov_b32_e32 v13, v125
	v_mov_b32_e32 v12, v125
	v_mov_b32_e32 v11, v125
	v_mov_b32_e32 v10, v125
	v_mov_b32_e32 v57, v125
	v_mov_b32_e32 v56, v125
	v_mov_b32_e32 v55, v125
	v_mov_b32_e32 v54, v125
	v_mov_b32_e32 v53, v125
	v_mov_b32_e32 v52, v125
	v_mov_b32_e32 v51, v125
	v_mov_b32_e32 v50, v125
	v_mov_b32_e32 v41, v125
	v_mov_b32_e32 v40, v125
	v_mov_b32_e32 v39, v125
	v_mov_b32_e32 v38, v125
	v_mov_b32_e32 v37, v125
	v_mov_b32_e32 v36, v125
	v_mov_b32_e32 v35, v125
	v_mov_b32_e32 v34, v125
	v_mov_b32_e32 v25, v125
	v_mov_b32_e32 v24, v125
	v_mov_b32_e32 v23, v125
	v_mov_b32_e32 v22, v125
	v_mov_b32_e32 v21, v125
	v_mov_b32_e32 v20, v125
	v_mov_b32_e32 v19, v125
	v_mov_b32_e32 v18, v125
	v_mov_b32_e32 v9, v125
	v_mov_b32_e32 v8, v125
	v_mov_b32_e32 v7, v125
	v_mov_b32_e32 v6, v125
	v_mov_b32_e32 v5, v125
	v_mov_b32_e32 v4, v125
	v_mov_b32_e32 v3, v125
	v_mov_b32_e32 v2, v125
	s_cbranch_vccnz .LBB0_822
	s_add_u32 s38, s38, 0x80
	s_addc_u32 s39, s39, 0
	s_add_u32 s63, s40, 0x100
	v_mov_b64_e32 v[2:3], 0
	v_mov_b64_e32 v[4:5], 0
	v_mov_b64_e32 v[6:7], 0
	v_mov_b64_e32 v[8:9], 0
	v_mov_b64_e32 v[10:11], 0
	v_mov_b64_e32 v[12:13], 0
	v_mov_b64_e32 v[14:15], 0
	v_mov_b64_e32 v[16:17], 0
	v_mov_b64_e32 v[18:19], 0
	v_mov_b64_e32 v[20:21], 0
	v_mov_b64_e32 v[22:23], 0
	v_mov_b64_e32 v[24:25], 0
	v_mov_b64_e32 v[26:27], 0
	v_mov_b64_e32 v[28:29], 0
	v_mov_b64_e32 v[30:31], 0
	v_mov_b64_e32 v[32:33], 0
	v_mov_b64_e32 v[34:35], 0
	v_mov_b64_e32 v[36:37], 0
	v_mov_b64_e32 v[38:39], 0
	v_mov_b64_e32 v[40:41], 0
	v_mov_b64_e32 v[42:43], 0
	v_mov_b64_e32 v[44:45], 0
	v_mov_b64_e32 v[46:47], 0
	v_mov_b64_e32 v[48:49], 0
	v_mov_b64_e32 v[50:51], 0
	v_mov_b64_e32 v[52:53], 0
	v_mov_b64_e32 v[54:55], 0
	v_mov_b64_e32 v[56:57], 0
	v_mov_b64_e32 v[58:59], 0
	v_mov_b64_e32 v[60:61], 0
	v_mov_b64_e32 v[62:63], 0
	v_mov_b64_e32 v[64:65], 0
	v_mov_b64_e32 v[66:67], 0
	v_mov_b64_e32 v[68:69], 0
	v_mov_b64_e32 v[70:71], 0
	v_mov_b64_e32 v[72:73], 0
	v_mov_b64_e32 v[74:75], 0
	v_mov_b64_e32 v[76:77], 0
	v_mov_b64_e32 v[78:79], 0
	v_mov_b64_e32 v[80:81], 0
	v_mov_b64_e32 v[82:83], 0
	v_mov_b64_e32 v[84:85], 0
	v_mov_b64_e32 v[86:87], 0
	v_mov_b64_e32 v[88:89], 0
	v_mov_b64_e32 v[90:91], 0
	v_mov_b64_e32 v[92:93], 0
	v_mov_b64_e32 v[94:95], 0
	v_mov_b64_e32 v[96:97], 0
	v_mov_b64_e32 v[98:99], 0
	v_mov_b64_e32 v[100:101], 0
	v_mov_b64_e32 v[102:103], 0
	v_mov_b64_e32 v[104:105], 0
	v_mov_b64_e32 v[106:107], 0
	v_mov_b64_e32 v[108:109], 0
	v_mov_b64_e32 v[110:111], 0
	v_mov_b64_e32 v[112:113], 0
	v_mov_b64_e32 v[114:115], 0
	v_mov_b64_e32 v[116:117], 0
	v_mov_b64_e32 v[118:119], 0
	v_mov_b64_e32 v[120:121], 0
	v_mov_b64_e32 v[122:123], 0
	v_mov_b64_e32 v[124:125], 0
	v_mov_b64_e32 v[126:127], 0
	v_mov_b64_e32 v[128:129], 0
	s_addc_u32 s64, s41, 0
	s_mov_b32 s40, 0
	.p2alignl 6, 3212836864

;     __device__ __forceinline__ bool next(int i, Unit& u) const { const int L = i * G + c; if (L >= nM * nN * ng) return false; const int per = nM * nN, r = L % per; u.g = L / per; u.pn = r / nM; u.pm = r % nM; return true; }
; template <class Epi, class Sched, bool ALIGN_EPI = false, bool SP2 = false>
; __device__ __forceinline__ void gemm_phase(PG8_LAS unsigned char* lds, const Gemm g, const Sched& S, const Epi& E) {
;     ...
;         const bool has_next = S.next(ui + 1, nxt);
;         const char* nA = has_next ? (const char*)g.A + (size_t)nxt.g * g.gsA * 2 + (size_t)nxt.pm * tstepA : cA; const char* nB = has_next ? (const char*)g.Bt + (size_t)nxt.g * g.gsB * 2 + (size_t)nxt.pn * tstepB : cB;
;     ...
; #pragma unroll
;         for (int a = 0; a < 2; ++a)
; #pragma unroll
;             for (int b = 0; b < 2; ++b)
; #pragma unroll
;                 for (int m = 0; m < 4; ++m)
; #pragma unroll
;                     for (int n = 0; n < 2; ++n) acc[a][b][m][n] = (f32x4){0.f, 0.f, 0.f, 0.f};
.LBB0_902:
	s_ashr_i32 s29, s28, 31
	s_lshl_b64 s[0:1], s[28:29], 19
	s_add_u32 s30, s10, s0
	s_addc_u32 s31, s11, s1
	s_and_b64 s[0:1], s[8:9], exec
	s_cselect_b32 s0, s31, s37
	s_cselect_b32 s1, s30, s36
	s_ashr_i32 s27, s26, 31
	s_lshl_b64 s[34:35], s[26:27], 19
	s_add_u32 s34, s3, s34
	s_addc_u32 s35, s42, s35
	s_and_b64 s[40:41], s[8:9], exec
	s_cselect_b32 s2, s35, s39
	s_cselect_b32 s5, s34, s38
	s_add_u32 s36, s36, 0x40080
	s_addc_u32 s37, s37, 0
	s_add_u32 s27, s38, 0x100
	v_mov_b64_e32 v[2:3], 0
	v_mov_b64_e32 v[4:5], 0
	v_mov_b64_e32 v[6:7], 0
	v_mov_b64_e32 v[8:9], 0
	v_mov_b64_e32 v[10:11], 0
	v_mov_b64_e32 v[12:13], 0
	v_mov_b64_e32 v[14:15], 0
	v_mov_b64_e32 v[16:17], 0
	v_mov_b64_e32 v[18:19], 0
	v_mov_b64_e32 v[20:21], 0
	v_mov_b64_e32 v[22:23], 0
	v_mov_b64_e32 v[24:25], 0
	v_mov_b64_e32 v[26:27], 0
	v_mov_b64_e32 v[28:29], 0
	v_mov_b64_e32 v[30:31], 0
	v_mov_b64_e32 v[32:33], 0
	v_mov_b64_e32 v[34:35], 0
	v_mov_b64_e32 v[36:37], 0
	v_mov_b64_e32 v[38:39], 0
	v_mov_b64_e32 v[40:41], 0
	v_mov_b64_e32 v[42:43], 0
	v_mov_b64_e32 v[44:45], 0
	v_mov_b64_e32 v[46:47], 0
	v_mov_b64_e32 v[48:49], 0
	v_mov_b64_e32 v[50:51], 0
	v_mov_b64_e32 v[52:53], 0
	v_mov_b64_e32 v[54:55], 0
	v_mov_b64_e32 v[56:57], 0
	v_mov_b64_e32 v[58:59], 0
	v_mov_b64_e32 v[60:61], 0
	v_mov_b64_e32 v[62:63], 0
	v_mov_b64_e32 v[64:65], 0
	v_mov_b64_e32 v[66:67], 0
	v_mov_b64_e32 v[68:69], 0
	v_mov_b64_e32 v[70:71], 0
	v_mov_b64_e32 v[72:73], 0
	v_mov_b64_e32 v[74:75], 0
	v_mov_b64_e32 v[76:77], 0
	v_mov_b64_e32 v[78:79], 0
	v_mov_b64_e32 v[80:81], 0
	v_mov_b64_e32 v[82:83], 0
	v_mov_b64_e32 v[84:85], 0
	v_mov_b64_e32 v[86:87], 0
	v_mov_b64_e32 v[88:89], 0
	v_mov_b64_e32 v[90:91], 0
	v_mov_b64_e32 v[92:93], 0
	v_mov_b64_e32 v[94:95], 0
	v_mov_b64_e32 v[96:97], 0
	v_mov_b64_e32 v[98:99], 0
	v_mov_b64_e32 v[100:101], 0
	v_mov_b64_e32 v[102:103], 0
	v_mov_b64_e32 v[104:105], 0
	v_mov_b64_e32 v[106:107], 0
	v_mov_b64_e32 v[108:109], 0
	v_mov_b64_e32 v[110:111], 0
	v_mov_b64_e32 v[112:113], 0
	v_mov_b64_e32 v[114:115], 0
	v_mov_b64_e32 v[116:117], 0
	v_mov_b64_e32 v[118:119], 0
	v_mov_b64_e32 v[120:121], 0
	v_mov_b64_e32 v[122:123], 0
	v_mov_b64_e32 v[124:125], 0
	v_mov_b64_e32 v[126:127], 0
	v_mov_b64_e32 v[128:129], 0
	s_addc_u32 s29, s39, 0
	s_mov_b32 s33, -2
	s_waitcnt lgkmcnt(0)
	.p2alignl 6, 3212836864

;     __device__ __forceinline__ bool next(int i, Unit& u) const { const int L = i * G + c; if (L >= nM * nN * ng) return false; const int per = nM * nN, r = L % per; u.g = L / per; u.pn = r / nM; u.pm = r % nM; return true; }
; template <class Epi, class Sched, bool ALIGN_EPI = false, bool SP2 = false>
; __device__ __forceinline__ void gemm_phase(PG8_LAS unsigned char* lds, const Gemm g, const Sched& S, const Epi& E) {
;     ...
;         const bool has_next = S.next(ui + 1, nxt);
;         const char* nA = has_next ? (const char*)g.A + (size_t)nxt.g * g.gsA * 2 + (size_t)nxt.pm * tstepA : cA; const char* nB = has_next ? (const char*)g.Bt + (size_t)nxt.g * g.gsB * 2 + (size_t)nxt.pn * tstepB : cB;
;     ...
; #pragma unroll
;         for (int a = 0; a < 2; ++a)
; #pragma unroll
;             for (int b = 0; b < 2; ++b)
; #pragma unroll
;                 for (int m = 0; m < 4; ++m)
; #pragma unroll
;                     for (int n = 0; n < 2; ++n) acc[a][b][m][n] = (f32x4){0.f, 0.f, 0.f, 0.f};
.LBB0_988:
	s_ashr_i32 s19, s18, 31
	s_lshl_b64 s[20:21], s[18:19], 19
	s_add_u32 s20, s3, s20
	s_addc_u32 s21, s30, s21
	s_and_b64 s[22:23], s[6:7], exec
	s_cselect_b32 s1, s21, s25
	s_cselect_b32 s5, s20, s24
	s_ashr_i32 s17, s16, 31
	s_lshl_b64 s[22:23], s[16:17], 19
	s_add_u32 s22, s31, s22
	s_addc_u32 s23, s34, s23
	s_and_b64 s[28:29], s[6:7], exec
	s_cselect_b32 s17, s23, s27
	s_cselect_b32 s19, s22, s26
	s_add_u32 s24, s24, 0x40080
	s_addc_u32 s25, s25, 0
	s_add_u32 s55, s26, 0x100
	v_mov_b64_e32 v[2:3], 0
	v_mov_b64_e32 v[4:5], 0
	v_mov_b64_e32 v[6:7], 0
	v_mov_b64_e32 v[8:9], 0
	v_mov_b64_e32 v[10:11], 0
	v_mov_b64_e32 v[12:13], 0
	v_mov_b64_e32 v[14:15], 0
	v_mov_b64_e32 v[16:17], 0
	v_mov_b64_e32 v[18:19], 0
	v_mov_b64_e32 v[20:21], 0
	v_mov_b64_e32 v[22:23], 0
	v_mov_b64_e32 v[24:25], 0
	v_mov_b64_e32 v[26:27], 0
	v_mov_b64_e32 v[28:29], 0
	v_mov_b64_e32 v[30:31], 0
	v_mov_b64_e32 v[32:33], 0
	v_mov_b64_e32 v[34:35], 0
	v_mov_b64_e32 v[36:37], 0
	v_mov_b64_e32 v[38:39], 0
	v_mov_b64_e32 v[40:41], 0
	v_mov_b64_e32 v[42:43], 0
	v_mov_b64_e32 v[44:45], 0
	v_mov_b64_e32 v[46:47], 0
	v_mov_b64_e32 v[48:49], 0
	v_mov_b64_e32 v[50:51], 0
	v_mov_b64_e32 v[52:53], 0
	v_mov_b64_e32 v[54:55], 0
	v_mov_b64_e32 v[56:57], 0
	v_mov_b64_e32 v[58:59], 0
	v_mov_b64_e32 v[60:61], 0
	v_mov_b64_e32 v[62:63], 0
	v_mov_b64_e32 v[64:65], 0
	v_mov_b64_e32 v[66:67], 0
	v_mov_b64_e32 v[68:69], 0
	v_mov_b64_e32 v[70:71], 0
	v_mov_b64_e32 v[72:73], 0
	v_mov_b64_e32 v[74:75], 0
	v_mov_b64_e32 v[76:77], 0
	v_mov_b64_e32 v[78:79], 0
	v_mov_b64_e32 v[80:81], 0
	v_mov_b64_e32 v[82:83], 0
	v_mov_b64_e32 v[84:85], 0
	v_mov_b64_e32 v[86:87], 0
	v_mov_b64_e32 v[88:89], 0
	v_mov_b64_e32 v[90:91], 0
	v_mov_b64_e32 v[92:93], 0
	v_mov_b64_e32 v[94:95], 0
	v_mov_b64_e32 v[96:97], 0
	v_mov_b64_e32 v[98:99], 0
	v_mov_b64_e32 v[100:101], 0
	v_mov_b64_e32 v[102:103], 0
	v_mov_b64_e32 v[104:105], 0
	v_mov_b64_e32 v[106:107], 0
	v_mov_b64_e32 v[108:109], 0
	v_mov_b64_e32 v[110:111], 0
	v_mov_b64_e32 v[112:113], 0
	v_mov_b64_e32 v[114:115], 0
	v_mov_b64_e32 v[116:117], 0
	v_mov_b64_e32 v[118:119], 0
	v_mov_b64_e32 v[120:121], 0
	v_mov_b64_e32 v[122:123], 0
	v_mov_b64_e32 v[124:125], 0
	v_mov_b64_e32 v[126:127], 0
	v_mov_b64_e32 v[128:129], 0
	s_addc_u32 s56, s27, 0
	s_mov_b32 s57, -2
	.p2alignl 6, 3212836864

; #define WAIT_BAR(N) asm volatile("s_waitcnt vmcnt(" #N ") lgkmcnt(0)\n\ts_barrier":::"memory")
;   #define DMA_K(t,slot) glds16(ksrc+(long)(t)*KVBLK*DM,(unsigned)__builtin_amdgcn_readfirstlane(kdst+(slot)))
;   #define DMA_V(t,slot) do{ glds16(vsrc+(long)(t)*KVBLK*DM,(unsigned)__builtin_amdgcn_readfirstlane(vdst+2*(slot))); glds16(vsrc+64+(long)(t)*KVBLK*DM,(unsigned)__builtin_amdgcn_readfirstlane(vdst+2*(slot)+8192)); }while(0)
;   #define CMASK(P0,P1,t) do{int jb_=(t)-(NT-4); if(jb_>=0)cmask(P0,P1,jb_,qrel,hi);}while(0)
;   #define START(P0,P1) do{ const float rm=rowmax(P0,P1); resc=false; mhat=fadd_s(mhat,rm); \
;     _Pragma("unroll") for(int r=0;r<16;++r){P0[r]=fsub_s(P0[r],mhat);P1[r]=fsub_s(P1[r],mhat);} \
;     _Pragma("unroll") for(int r=0;r<16;++r)P0[r]=__builtin_amdgcn_exp2f(P0[r]); }while(0)
;   #define ROT() do{sl_prev=sl_cur;sl_cur=sl_next;sl_next=(sl_next==(NSLOT-1)*SLOTB)?0:sl_next+SLOTB;}while(0)
;   #define CMASK(P0,P1,t) do{}while(0)
;   #define CMASK(P0,P1,t) do{int jb_=(t)-(NT-4); if(jb_>=0)cmask(P0,P1,jb_,qrel,hi);}while(0)
; template<int THRL,int MODE> __device__ __forceinline__ void attn_unit(int b,int qb,const bf16*Q,const bf16*__restrict__ K,const bf16*__restrict__ V,bf16*O,bf16*O2,char*shm,bf16*CM,float lam,const float*gn){
;     ...
;   f32x16 pA0,pA1,pB0,pB1;
;   int sl_prev=0,sl_cur=0,sl_next=SLOTB;
;     ...
;   DMA_K(2,2*SLOTB);
;   WAIT_BAR(4);
;   qkt(pA0,pA1,Kbase,qr,r32,hi);asm volatile("s_nop 15\n\ts_nop 7":"+v"(pA0),"+v"(pA1));CMASK(pA0,pA1,0);
;   START(pA0,pA1);
;   _Pragma("unroll") for(int r=0;r<16;++r)pA1[r]=__builtin_amdgcn_exp2f(pA1[r]);
;   WAIT_BAR(0);
;   DMA_K(3,0);DMA_V(1,SLOTB);
;   ROT();
;   kload8(kf,kp0+sl_cur);
;   WAIT_BAR(3);
.LBB0_1065:
	v_lshlrev_b32_e32 v2, 1, v36
	v_and_b32_e32 v245, 32, v2
	v_lshlrev_b32_e32 v2, 4, v36
	v_and_b32_e32 v2, 0xc0, v2
	v_lshl_or_b32 v243, v214, 8, v2
	v_add_u32_e32 v2, 0, v245
	v_add3_u32 v249, v2, v242, v243
	v_max3_f32 v2, v20, v21, v4
	v_max3_f32 v36, v22, v23, v5
	s_and_b32 s1, s1, 0x3fffffc0
	v_max3_f32 v2, v2, v6, v7
	v_max3_f32 v36, v36, v26, v27
	s_lshl_b32 s1, s1, 2
	v_max3_f32 v2, v2, v24, v25
	v_max3_f32 v36, v36, v10, v11
	s_add_i32 s2, s64, 0x100
	v_max3_f32 v2, v2, v8, v9
	v_max3_f32 v36, v36, v30, v31
	s_add_i32 s66, s1, 0
	v_max3_f32 v2, v2, v28, v29
	v_max3_f32 v36, v36, v14, v15
	s_add_i32 s66, s66, 0x12000
	v_max3_f32 v2, v2, v12, v13
	v_max3_f32 v36, v36, v34, v35
	s_lshr_b32 s63, s2, 6
	v_max3_f32 v2, v2, v32, v33
	v_max3_f32 v36, v36, v18, v19
	s_waitcnt vmcnt(0) lgkmcnt(0)
	s_barrier
	s_cmp_lg_u32 0, -1
	v_max3_f32 v2, v2, v16, v17
	s_mov_b32 s14, 1
	v_max_f32_e32 v2, v2, v36
	s_mov_b32 s1, 0
	v_mov_b32_e32 v36, v2
	s_nop 1
	v_permlane32_swap_b32_e32 v2, v36
	v_max_f32_e32 v2, v2, v36
	v_lshlrev_b32_e32 v250, 4, v214
	v_add_f32_e32 v246, v3, v2
	v_lshl_add_u32 v244, v239, 2, s66
	v_sub_f32_e32 v4, v4, v246
	v_sub_f32_e32 v5, v5, v246
	v_sub_f32_e32 v2, v20, v246
	v_sub_f32_e32 v20, v21, v246
	v_sub_f32_e32 v21, v22, v246
	v_sub_f32_e32 v6, v6, v246
	s_nop 0
	v_exp_f32_e32 v82, v4
	v_exp_f32_e32 v83, v5
	v_lshl_add_u64 v[4:5], v[224:225], 0, s[22:23]
	s_mov_b32 s2, m0
	s_mov_b32 m0, s67
	s_nop 0
	global_load_lds_dwordx4 v[4:5], off
	s_mov_b32 m0, s2
	s_cselect_b32 s2, 0, 0
	s_add_i32 s0, s2, s0
	v_lshl_add_u64 v[4:5], v[226:227], 0, s[18:19]
	s_add_i32 s2, s0, 0xa000
	s_mov_b32 s6, m0
	s_mov_b32 m0, s2
	s_nop 0
	global_load_lds_dwordx4 v[4:5], off
	s_mov_b32 m0, s6
	v_lshl_add_u64 v[4:5], v[226:227], 0, s[24:25]
	s_add_i32 s0, s0, 0xc000
	s_mov_b32 s2, m0
	s_mov_b32 m0, s0
	s_nop 0
	global_load_lds_dwordx4 v[4:5], off
	s_mov_b32 m0, s2
	ds_read_b128 v[206:209], v248 offset:8192
	ds_read_b128 v[202:205], v248 offset:8704
	ds_read_b128 v[198:201], v248 offset:10240
	ds_read_b128 v[194:197], v248 offset:10752
	ds_read_b128 v[190:193], v248 offset:12288
	ds_read_b128 v[186:189], v248 offset:12800
	ds_read_b128 v[182:185], v248 offset:14336
	ds_read_b128 v[178:181], v248 offset:14848
	v_sub_f32_e32 v22, v23, v246
	v_sub_f32_e32 v7, v7, v246
	v_sub_f32_e32 v23, v24, v246
	v_sub_f32_e32 v8, v8, v246
	v_sub_f32_e32 v24, v25, v246
	v_sub_f32_e32 v9, v9, v246
	v_sub_f32_e32 v25, v26, v246
	v_sub_f32_e32 v10, v10, v246
	v_sub_f32_e32 v26, v27, v246
	v_sub_f32_e32 v11, v11, v246
	v_sub_f32_e32 v27, v28, v246
	v_sub_f32_e32 v12, v12, v246
	v_sub_f32_e32 v28, v29, v246
	v_sub_f32_e32 v13, v13, v246
	v_sub_f32_e32 v29, v30, v246
	v_sub_f32_e32 v14, v14, v246
	v_sub_f32_e32 v30, v31, v246
	v_sub_f32_e32 v15, v15, v246
	v_sub_f32_e32 v31, v32, v246
	v_sub_f32_e32 v16, v16, v246
	v_sub_f32_e32 v32, v33, v246
	v_sub_f32_e32 v17, v17, v246
	v_sub_f32_e32 v33, v34, v246
	v_sub_f32_e32 v18, v18, v246
	v_sub_f32_e32 v34, v35, v246
	v_sub_f32_e32 v19, v19, v246
	v_exp_f32_e32 v98, v2
	v_exp_f32_e32 v99, v20
	v_exp_f32_e32 v100, v21
	v_exp_f32_e32 v101, v22
	v_exp_f32_e32 v102, v23
	v_exp_f32_e32 v103, v24
	v_exp_f32_e32 v104, v25
	v_exp_f32_e32 v105, v26
	v_exp_f32_e32 v106, v27
	v_exp_f32_e32 v107, v28
	v_exp_f32_e32 v108, v29
	v_exp_f32_e32 v109, v30
	v_exp_f32_e32 v110, v31
	v_exp_f32_e32 v111, v32
	v_exp_f32_e32 v112, v33
	v_exp_f32_e32 v113, v34
	v_exp_f32_e32 v84, v6
	v_exp_f32_e32 v85, v7
	v_exp_f32_e32 v86, v8
	v_exp_f32_e32 v87, v9
	v_exp_f32_e32 v88, v10
	v_exp_f32_e32 v89, v11
	v_exp_f32_e32 v90, v12
	v_exp_f32_e32 v91, v13
	v_exp_f32_e32 v92, v14
	v_exp_f32_e32 v93, v15
	v_exp_f32_e32 v94, v16
	v_exp_f32_e32 v95, v17
	v_exp_f32_e32 v96, v18
	v_exp_f32_e32 v97, v19
	s_waitcnt vmcnt(3) lgkmcnt(0)
	s_barrier
	v_cndmask_b32_e64 v2, 0, 1, s[8:9]
	v_cmp_ne_u32_e64 s[6:7], 1, v2
	s_andn2_b64 vcc, exec, s[8:9]
	v_cmp_gt_u32_e64 s[8:9], 32, v238
	s_cbranch_vccnz .LBB0_1081
	v_mov_b32_e32 v16, v3
	v_mov_b32_e32 v17, v3
	v_mov_b32_e32 v2, v3
	v_mov_b32_e32 v4, v3
	v_mov_b32_e32 v5, v3
	v_mov_b32_e32 v6, v3
	v_mov_b32_e32 v7, v3
	v_mov_b32_e32 v8, v3
	v_mov_b32_e32 v9, v3
	v_mov_b32_e32 v10, v3
	v_mov_b32_e32 v11, v3
	v_mov_b32_e32 v12, v3
	v_mov_b32_e32 v13, v3
	v_mov_b32_e32 v14, v3
	v_mov_b32_e32 v15, v3
	v_mov_b64_e32 v[80:81], v[16:17]
	v_mov_b64_e32 v[64:65], v[16:17]
	v_mov_b64_e32 v[48:49], v[16:17]
	v_mov_b64_e32 v[32:33], v[16:17]
	s_mov_b32 s33, 0
	s_movk_i32 s1, 0x4000
	s_movk_i32 s14, 0x2000
	v_mov_b32_e32 v251, 0
	s_mov_b32 s2, 6
	s_mov_b64 s[38:39], 0
	v_mov_b64_e32 v[78:79], v[14:15]
	v_mov_b64_e32 v[76:77], v[12:13]
	v_mov_b64_e32 v[74:75], v[10:11]
	v_mov_b64_e32 v[72:73], v[8:9]
	v_mov_b64_e32 v[70:71], v[6:7]
	v_mov_b64_e32 v[68:69], v[4:5]
	v_mov_b64_e32 v[66:67], v[2:3]
	v_mov_b64_e32 v[62:63], v[14:15]
	v_mov_b64_e32 v[60:61], v[12:13]
	v_mov_b64_e32 v[58:59], v[10:11]
	v_mov_b64_e32 v[56:57], v[8:9]
	v_mov_b64_e32 v[54:55], v[6:7]
	v_mov_b64_e32 v[52:53], v[4:5]
	v_mov_b64_e32 v[50:51], v[2:3]
	v_mov_b64_e32 v[46:47], v[14:15]
	v_mov_b64_e32 v[44:45], v[12:13]
	v_mov_b64_e32 v[42:43], v[10:11]
	v_mov_b64_e32 v[40:41], v[8:9]
	v_mov_b64_e32 v[38:39], v[6:7]
	v_mov_b64_e32 v[36:37], v[4:5]
	v_mov_b64_e32 v[34:35], v[2:3]
	v_mov_b64_e32 v[30:31], v[14:15]
	v_mov_b64_e32 v[28:29], v[12:13]
	v_mov_b64_e32 v[26:27], v[10:11]
	v_mov_b64_e32 v[24:25], v[8:9]
	v_mov_b64_e32 v[22:23], v[6:7]
	v_mov_b64_e32 v[20:21], v[4:5]
	v_mov_b64_e32 v[18:19], v[2:3]
	.p2alignl 6, 3212836864

; #define WAIT_BAR(N) asm volatile("s_waitcnt vmcnt(" #N ") lgkmcnt(0)\n\ts_barrier":::"memory")
;   #define DMA_K(t,slot) glds16(ksrc+(long)(t)*KVBLK*DM,(unsigned)__builtin_amdgcn_readfirstlane(kdst+(slot)))
;   #define DMA_V(t,slot) do{ glds16(vsrc+(long)(t)*KVBLK*DM,(unsigned)__builtin_amdgcn_readfirstlane(vdst+2*(slot))); glds16(vsrc+64+(long)(t)*KVBLK*DM,(unsigned)__builtin_amdgcn_readfirstlane(vdst+2*(slot)+8192)); }while(0)
;   #define CMASK(P0,P1,t) do{int jb_=(t)-(NT-4); if(jb_>=0)cmask(P0,P1,jb_,qrel,hi);}while(0)
;   #define START(P0,P1) do{ const float rm=rowmax(P0,P1); resc=false; mhat=fadd_s(mhat,rm); \
;     _Pragma("unroll") for(int r=0;r<16;++r){P0[r]=fsub_s(P0[r],mhat);P1[r]=fsub_s(P1[r],mhat);} \
;     _Pragma("unroll") for(int r=0;r<16;++r)P0[r]=__builtin_amdgcn_exp2f(P0[r]); }while(0)
;   #define ROT() do{sl_prev=sl_cur;sl_cur=sl_next;sl_next=(sl_next==(NSLOT-1)*SLOTB)?0:sl_next+SLOTB;}while(0)
;   #define CMASK(P0,P1,t) do{}while(0)
;   #define CMASK(P0,P1,t) do{int jb_=(t)-(NT-4); if(jb_>=0)cmask(P0,P1,jb_,qrel,hi);}while(0)
; template<int THRL,int MODE> __device__ __forceinline__ void attn_unit(int b,int qb,const bf16*Q,const bf16*__restrict__ K,const bf16*__restrict__ V,bf16*O,bf16*O2,char*shm,bf16*CM,float lam,const float*gn){
;     ...
;   f32x16 pA0,pA1,pB0,pB1;
;   int sl_prev=0,sl_cur=0,sl_next=SLOTB;
;     ...
;   DMA_K(2,2*SLOTB);
;   WAIT_BAR(4);
;   qkt(pA0,pA1,Kbase,qr,r32,hi);asm volatile("s_nop 15\n\ts_nop 7":"+v"(pA0),"+v"(pA1));CMASK(pA0,pA1,0);
;   START(pA0,pA1);
;   _Pragma("unroll") for(int r=0;r<16;++r)pA1[r]=__builtin_amdgcn_exp2f(pA1[r]);
;   WAIT_BAR(0);
;   DMA_K(3,0);DMA_V(1,SLOTB);
;   ROT();
;   kload8(kf,kp0+sl_cur);
;   WAIT_BAR(3);
.LBB0_1094:
	v_lshlrev_b32_e32 v2, 1, v36
	v_and_b32_e32 v245, 32, v2
	v_lshlrev_b32_e32 v2, 4, v36
	v_and_b32_e32 v2, 0xc0, v2
	v_lshl_or_b32 v243, v214, 8, v2
	v_add_u32_e32 v2, 0, v245
	v_add3_u32 v249, v2, v242, v243
	v_max3_f32 v2, v20, v21, v4
	v_max3_f32 v36, v22, v23, v5
	s_and_b32 s1, s1, 0x3fffffc0
	v_max3_f32 v2, v2, v6, v7
	v_max3_f32 v36, v36, v26, v27
	s_lshl_b32 s1, s1, 2
	v_max3_f32 v2, v2, v24, v25
	v_max3_f32 v36, v36, v10, v11
	s_add_i32 s45, s1, 0
	v_max3_f32 v2, v2, v8, v9
	v_max3_f32 v36, v36, v30, v31
	s_add_i32 s45, s45, 0x12000
	v_max3_f32 v2, v2, v28, v29
	v_max3_f32 v36, v36, v14, v15
	s_waitcnt vmcnt(0) lgkmcnt(0)
	s_barrier
	s_cmp_lg_u32 0, -1
	v_max3_f32 v2, v2, v12, v13
	v_max3_f32 v36, v36, v34, v35
	s_mov_b32 s14, 1
	v_max3_f32 v2, v2, v32, v33
	v_max3_f32 v36, v36, v18, v19
	s_mov_b32 s1, 0
	v_max3_f32 v2, v2, v16, v17
	v_lshlrev_b32_e32 v250, 4, v214
	v_max_f32_e32 v2, v2, v36
	v_lshl_add_u32 v244, v239, 2, s45
	v_mov_b32_e32 v36, v2
	s_nop 1
	v_permlane32_swap_b32_e32 v2, v36
	v_max_f32_e32 v2, v2, v36
	s_nop 0
	v_add_f32_e32 v246, v3, v2
	s_nop 0
	v_sub_f32_e32 v4, v4, v246
	v_sub_f32_e32 v5, v5, v246
	v_sub_f32_e32 v2, v20, v246
	v_sub_f32_e32 v20, v21, v246
	v_sub_f32_e32 v21, v22, v246
	v_sub_f32_e32 v6, v6, v246
	s_nop 0
	v_exp_f32_e32 v82, v4
	v_exp_f32_e32 v83, v5
	v_lshl_add_u64 v[4:5], v[224:225], 0, s[22:23]
	s_mov_b32 s2, m0
	s_mov_b32 m0, s46
	s_nop 0
	global_load_lds_dwordx4 v[4:5], off
	s_mov_b32 m0, s2
	s_cselect_b32 s2, 0, 0
	s_add_i32 s0, s2, s0
	v_lshl_add_u64 v[4:5], v[226:227], 0, s[18:19]
	s_add_i32 s2, s0, 0xa000
	s_mov_b32 s4, m0
	s_mov_b32 m0, s2
	s_nop 0
	global_load_lds_dwordx4 v[4:5], off
	s_mov_b32 m0, s4
	v_lshl_add_u64 v[4:5], v[226:227], 0, s[24:25]
	s_add_i32 s0, s0, 0xc000
	s_mov_b32 s2, m0
	s_mov_b32 m0, s0
	s_nop 0
	global_load_lds_dwordx4 v[4:5], off
	s_mov_b32 m0, s2
	ds_read_b128 v[206:209], v248 offset:8192
	ds_read_b128 v[202:205], v248 offset:8704
	ds_read_b128 v[198:201], v248 offset:10240
	ds_read_b128 v[194:197], v248 offset:10752
	ds_read_b128 v[190:193], v248 offset:12288
	ds_read_b128 v[186:189], v248 offset:12800
	ds_read_b128 v[182:185], v248 offset:14336
	ds_read_b128 v[178:181], v248 offset:14848
	v_sub_f32_e32 v22, v23, v246
	v_sub_f32_e32 v7, v7, v246
	v_sub_f32_e32 v23, v24, v246
	v_sub_f32_e32 v8, v8, v246
	v_sub_f32_e32 v24, v25, v246
	v_sub_f32_e32 v9, v9, v246
	v_sub_f32_e32 v25, v26, v246
	v_sub_f32_e32 v10, v10, v246
	v_sub_f32_e32 v26, v27, v246
	v_sub_f32_e32 v11, v11, v246
	v_sub_f32_e32 v27, v28, v246
	v_sub_f32_e32 v12, v12, v246
	v_sub_f32_e32 v28, v29, v246
	v_sub_f32_e32 v13, v13, v246
	v_sub_f32_e32 v29, v30, v246
	v_sub_f32_e32 v14, v14, v246
	v_sub_f32_e32 v30, v31, v246
	v_sub_f32_e32 v15, v15, v246
	v_sub_f32_e32 v31, v32, v246
	v_sub_f32_e32 v16, v16, v246
	v_sub_f32_e32 v32, v33, v246
	v_sub_f32_e32 v17, v17, v246
	v_sub_f32_e32 v33, v34, v246
	v_sub_f32_e32 v18, v18, v246
	v_sub_f32_e32 v34, v35, v246
	v_sub_f32_e32 v19, v19, v246
	v_exp_f32_e32 v98, v2
	v_exp_f32_e32 v99, v20
	v_exp_f32_e32 v100, v21
	v_exp_f32_e32 v101, v22
	v_exp_f32_e32 v102, v23
	v_exp_f32_e32 v103, v24
	v_exp_f32_e32 v104, v25
	v_exp_f32_e32 v105, v26
	v_exp_f32_e32 v106, v27
	v_exp_f32_e32 v107, v28
	v_exp_f32_e32 v108, v29
	v_exp_f32_e32 v109, v30
	v_exp_f32_e32 v110, v31
	v_exp_f32_e32 v111, v32
	v_exp_f32_e32 v112, v33
	v_exp_f32_e32 v113, v34
	v_exp_f32_e32 v84, v6
	v_exp_f32_e32 v85, v7
	v_exp_f32_e32 v86, v8
	v_exp_f32_e32 v87, v9
	v_exp_f32_e32 v88, v10
	v_exp_f32_e32 v89, v11
	v_exp_f32_e32 v90, v12
	v_exp_f32_e32 v91, v13
	v_exp_f32_e32 v92, v14
	v_exp_f32_e32 v93, v15
	v_exp_f32_e32 v94, v16
	v_exp_f32_e32 v95, v17
	v_exp_f32_e32 v96, v18
	v_exp_f32_e32 v97, v19
	s_waitcnt vmcnt(3) lgkmcnt(0)
	s_barrier
	s_and_b64 vcc, exec, s[6:7]
	v_cmp_gt_u32_e64 s[6:7], 32, v238
	s_cbranch_vccnz .LBB0_1160
	v_mov_b32_e32 v16, v3
	v_mov_b32_e32 v17, v3
	v_mov_b32_e32 v2, v3
	v_mov_b32_e32 v4, v3
	v_mov_b32_e32 v5, v3
	v_mov_b32_e32 v6, v3
	v_mov_b32_e32 v7, v3
	v_mov_b32_e32 v8, v3
	v_mov_b32_e32 v9, v3
	v_mov_b32_e32 v10, v3
	v_mov_b32_e32 v11, v3
	v_mov_b32_e32 v12, v3
	v_mov_b32_e32 v13, v3
	v_mov_b32_e32 v14, v3
	v_mov_b32_e32 v15, v3
	v_mov_b64_e32 v[80:81], v[16:17]
	v_mov_b64_e32 v[64:65], v[16:17]
	v_mov_b64_e32 v[48:49], v[16:17]
	v_mov_b64_e32 v[32:33], v[16:17]
	s_mov_b32 s8, 0
	s_movk_i32 s1, 0x4000
	s_movk_i32 s14, 0x2000
	v_mov_b32_e32 v251, 0
	s_mov_b32 s2, 6
	s_mov_b64 s[4:5], 0
	v_mov_b64_e32 v[78:79], v[14:15]
	v_mov_b64_e32 v[76:77], v[12:13]
	v_mov_b64_e32 v[74:75], v[10:11]
	v_mov_b64_e32 v[72:73], v[8:9]
	v_mov_b64_e32 v[70:71], v[6:7]
	v_mov_b64_e32 v[68:69], v[4:5]
	v_mov_b64_e32 v[66:67], v[2:3]
	v_mov_b64_e32 v[62:63], v[14:15]
	v_mov_b64_e32 v[60:61], v[12:13]
	v_mov_b64_e32 v[58:59], v[10:11]
	v_mov_b64_e32 v[56:57], v[8:9]
	v_mov_b64_e32 v[54:55], v[6:7]
	v_mov_b64_e32 v[52:53], v[4:5]
	v_mov_b64_e32 v[50:51], v[2:3]
	v_mov_b64_e32 v[46:47], v[14:15]
	v_mov_b64_e32 v[44:45], v[12:13]
	v_mov_b64_e32 v[42:43], v[10:11]
	v_mov_b64_e32 v[40:41], v[8:9]
	v_mov_b64_e32 v[38:39], v[6:7]
	v_mov_b64_e32 v[36:37], v[4:5]
	v_mov_b64_e32 v[34:35], v[2:3]
	v_mov_b64_e32 v[30:31], v[14:15]
	v_mov_b64_e32 v[28:29], v[12:13]
	v_mov_b64_e32 v[26:27], v[10:11]
	v_mov_b64_e32 v[24:25], v[8:9]
	v_mov_b64_e32 v[22:23], v[6:7]
	v_mov_b64_e32 v[20:21], v[4:5]
	v_mov_b64_e32 v[18:19], v[2:3]
	.p2alignl 6, 3212836864

; #define WAIT_BAR(N) asm volatile("s_waitcnt vmcnt(" #N ") lgkmcnt(0)\n\ts_barrier":::"memory")
;   #define DMA_K(t,slot) glds16(ksrc+(long)(t)*KVBLK*DM,(unsigned)__builtin_amdgcn_readfirstlane(kdst+(slot)))
;   #define DMA_V(t,slot) do{ glds16(vsrc+(long)(t)*KVBLK*DM,(unsigned)__builtin_amdgcn_readfirstlane(vdst+2*(slot))); glds16(vsrc+64+(long)(t)*KVBLK*DM,(unsigned)__builtin_amdgcn_readfirstlane(vdst+2*(slot)+8192)); }while(0)
;   #define CMASK(P0,P1,t) do{int jb_=(t)-(NT-4); if(jb_>=0)cmask(P0,P1,jb_,qrel,hi);}while(0)
;   #define START(P0,P1) do{ const float rm=rowmax(P0,P1); resc=false; mhat=fadd_s(mhat,rm); \
;     _Pragma("unroll") for(int r=0;r<16;++r){P0[r]=fsub_s(P0[r],mhat);P1[r]=fsub_s(P1[r],mhat);} \
;     _Pragma("unroll") for(int r=0;r<16;++r)P0[r]=__builtin_amdgcn_exp2f(P0[r]); }while(0)
;   #define ROT() do{sl_prev=sl_cur;sl_cur=sl_next;sl_next=(sl_next==(NSLOT-1)*SLOTB)?0:sl_next+SLOTB;}while(0)
;   #define CMASK(P0,P1,t) do{}while(0)
;   #define CMASK(P0,P1,t) do{int jb_=(t)-(NT-4); if(jb_>=0)cmask(P0,P1,jb_,qrel,hi);}while(0)
; template<int THRL,int MODE> __device__ __forceinline__ void attn_unit(int b,int qb,const bf16*Q,const bf16*__restrict__ K,const bf16*__restrict__ V,bf16*O,bf16*O2,char*shm,bf16*CM,float lam,const float*gn){
;     ...
;   f32x16 pA0,pA1,pB0,pB1;
;   int sl_prev=0,sl_cur=0,sl_next=SLOTB;
;     ...
;   DMA_K(2,2*SLOTB);
;   WAIT_BAR(4);
;   qkt(pA0,pA1,Kbase,qr,r32,hi);asm volatile("s_nop 15\n\ts_nop 7":"+v"(pA0),"+v"(pA1));CMASK(pA0,pA1,0);
;   START(pA0,pA1);
;   _Pragma("unroll") for(int r=0;r<16;++r)pA1[r]=__builtin_amdgcn_exp2f(pA1[r]);
;   WAIT_BAR(0);
;   DMA_K(3,0);DMA_V(1,SLOTB);
;   ROT();
;   kload8(kf,kp0+sl_cur);
;   WAIT_BAR(3);
.LBB0_1232:
	v_lshlrev_b32_e32 v2, 1, v36
	v_and_b32_e32 v245, 32, v2
	v_lshlrev_b32_e32 v2, 4, v36
	v_and_b32_e32 v2, 0xc0, v2
	v_lshl_or_b32 v243, v214, 8, v2
	v_add_u32_e32 v2, 0, v245
	v_add3_u32 v249, v2, v242, v243
	v_max3_f32 v2, v20, v21, v4
	v_max3_f32 v36, v22, v23, v5
	s_and_b32 s1, s1, 0x3fffffc0
	v_max3_f32 v2, v2, v6, v7
	v_max3_f32 v36, v36, v26, v27
	s_lshl_b32 s1, s1, 2
	v_max3_f32 v2, v2, v24, v25
	v_max3_f32 v36, v36, v10, v11
	s_add_i32 s2, s85, 0x100
	v_max3_f32 v2, v2, v8, v9
	v_max3_f32 v36, v36, v30, v31
	s_add_i32 s89, s1, 0
	v_max3_f32 v2, v2, v28, v29
	v_max3_f32 v36, v36, v14, v15
	s_add_i32 s89, s89, 0x12000
	v_max3_f32 v2, v2, v12, v13
	v_max3_f32 v36, v36, v34, v35
	s_lshr_b32 s75, s2, 6
	v_max3_f32 v2, v2, v32, v33
	v_max3_f32 v36, v36, v18, v19
	s_waitcnt vmcnt(0) lgkmcnt(0)
	s_barrier
	s_cmp_lg_u32 0, -1
	v_max3_f32 v2, v2, v16, v17
	s_mov_b32 s16, 1
	v_max_f32_e32 v2, v2, v36
	s_mov_b32 s1, 0
	v_mov_b32_e32 v36, v2
	s_nop 1
	v_permlane32_swap_b32_e32 v2, v36
	v_max_f32_e32 v2, v2, v36
	v_lshlrev_b32_e32 v250, 4, v214
	v_add_f32_e32 v246, v3, v2
	v_lshl_add_u32 v244, v239, 2, s89
	v_sub_f32_e32 v4, v4, v246
	v_sub_f32_e32 v5, v5, v246
	v_sub_f32_e32 v2, v20, v246
	v_sub_f32_e32 v20, v21, v246
	v_sub_f32_e32 v21, v22, v246
	v_sub_f32_e32 v6, v6, v246
	s_nop 0
	v_exp_f32_e32 v82, v4
	v_exp_f32_e32 v83, v5
	v_lshl_add_u64 v[4:5], v[224:225], 0, s[24:25]
	s_mov_b32 s2, m0
	s_mov_b32 m0, s90
	s_nop 0
	global_load_lds_dwordx4 v[4:5], off
	s_mov_b32 m0, s2
	s_cselect_b32 s2, 0, 0
	s_add_i32 s0, s2, s0
	v_lshl_add_u64 v[4:5], v[226:227], 0, s[20:21]
	s_add_i32 s2, s0, 0xa000
	s_mov_b32 s6, m0
	s_mov_b32 m0, s2
	s_nop 0
	global_load_lds_dwordx4 v[4:5], off
	s_mov_b32 m0, s6
	v_lshl_add_u64 v[4:5], v[226:227], 0, s[26:27]
	s_add_i32 s0, s0, 0xc000
	s_mov_b32 s2, m0
	s_mov_b32 m0, s0
	s_nop 0
	global_load_lds_dwordx4 v[4:5], off
	s_mov_b32 m0, s2
	ds_read_b128 v[206:209], v248 offset:8192
	ds_read_b128 v[202:205], v248 offset:8704
	ds_read_b128 v[198:201], v248 offset:10240
	ds_read_b128 v[194:197], v248 offset:10752
	ds_read_b128 v[190:193], v248 offset:12288
	ds_read_b128 v[186:189], v248 offset:12800
	ds_read_b128 v[182:185], v248 offset:14336
	ds_read_b128 v[178:181], v248 offset:14848
	v_sub_f32_e32 v22, v23, v246
	v_sub_f32_e32 v7, v7, v246
	v_sub_f32_e32 v23, v24, v246
	v_sub_f32_e32 v8, v8, v246
	v_sub_f32_e32 v24, v25, v246
	v_sub_f32_e32 v9, v9, v246
	v_sub_f32_e32 v25, v26, v246
	v_sub_f32_e32 v10, v10, v246
	v_sub_f32_e32 v26, v27, v246
	v_sub_f32_e32 v11, v11, v246
	v_sub_f32_e32 v27, v28, v246
	v_sub_f32_e32 v12, v12, v246
	v_sub_f32_e32 v28, v29, v246
	v_sub_f32_e32 v13, v13, v246
	v_sub_f32_e32 v29, v30, v246
	v_sub_f32_e32 v14, v14, v246
	v_sub_f32_e32 v30, v31, v246
	v_sub_f32_e32 v15, v15, v246
	v_sub_f32_e32 v31, v32, v246
	v_sub_f32_e32 v16, v16, v246
	v_sub_f32_e32 v32, v33, v246
	v_sub_f32_e32 v17, v17, v246
	v_sub_f32_e32 v33, v34, v246
	v_sub_f32_e32 v18, v18, v246
	v_sub_f32_e32 v34, v35, v246
	v_sub_f32_e32 v19, v19, v246
	v_exp_f32_e32 v98, v2
	v_exp_f32_e32 v99, v20
	v_exp_f32_e32 v100, v21
	v_exp_f32_e32 v101, v22
	v_exp_f32_e32 v102, v23
	v_exp_f32_e32 v103, v24
	v_exp_f32_e32 v104, v25
	v_exp_f32_e32 v105, v26
	v_exp_f32_e32 v106, v27
	v_exp_f32_e32 v107, v28
	v_exp_f32_e32 v108, v29
	v_exp_f32_e32 v109, v30
	v_exp_f32_e32 v110, v31
	v_exp_f32_e32 v111, v32
	v_exp_f32_e32 v112, v33
	v_exp_f32_e32 v113, v34
	v_exp_f32_e32 v84, v6
	v_exp_f32_e32 v85, v7
	v_exp_f32_e32 v86, v8
	v_exp_f32_e32 v87, v9
	v_exp_f32_e32 v88, v10
	v_exp_f32_e32 v89, v11
	v_exp_f32_e32 v90, v12
	v_exp_f32_e32 v91, v13
	v_exp_f32_e32 v92, v14
	v_exp_f32_e32 v93, v15
	v_exp_f32_e32 v94, v16
	v_exp_f32_e32 v95, v17
	v_exp_f32_e32 v96, v18
	v_exp_f32_e32 v97, v19
	s_waitcnt vmcnt(3) lgkmcnt(0)
	s_barrier
	v_cndmask_b32_e64 v2, 0, 1, s[8:9]
	v_cmp_ne_u32_e64 s[6:7], 1, v2
	s_andn2_b64 vcc, exec, s[8:9]
	v_cmp_gt_u32_e64 s[8:9], 32, v238
	s_cbranch_vccnz .LBB0_1248
	v_mov_b32_e32 v16, v3
	v_mov_b32_e32 v17, v3
	v_mov_b32_e32 v2, v3
	v_mov_b32_e32 v4, v3
	v_mov_b32_e32 v5, v3
	v_mov_b32_e32 v6, v3
	v_mov_b32_e32 v7, v3
	v_mov_b32_e32 v8, v3
	v_mov_b32_e32 v9, v3
	v_mov_b32_e32 v10, v3
	v_mov_b32_e32 v11, v3
	v_mov_b32_e32 v12, v3
	v_mov_b32_e32 v13, v3
	v_mov_b32_e32 v14, v3
	v_mov_b32_e32 v15, v3
	v_mov_b64_e32 v[80:81], v[16:17]
	v_mov_b64_e32 v[64:65], v[16:17]
	v_mov_b64_e32 v[48:49], v[16:17]
	v_mov_b64_e32 v[32:33], v[16:17]
	s_mov_b32 s33, 0
	s_movk_i32 s1, 0x4000
	s_movk_i32 s16, 0x2000
	v_mov_b32_e32 v251, 0
	s_mov_b32 s2, 6
	s_mov_b64 s[44:45], 0
	v_mov_b64_e32 v[78:79], v[14:15]
	v_mov_b64_e32 v[76:77], v[12:13]
	v_mov_b64_e32 v[74:75], v[10:11]
	v_mov_b64_e32 v[72:73], v[8:9]
	v_mov_b64_e32 v[70:71], v[6:7]
	v_mov_b64_e32 v[68:69], v[4:5]
	v_mov_b64_e32 v[66:67], v[2:3]
	v_mov_b64_e32 v[62:63], v[14:15]
	v_mov_b64_e32 v[60:61], v[12:13]
	v_mov_b64_e32 v[58:59], v[10:11]
	v_mov_b64_e32 v[56:57], v[8:9]
	v_mov_b64_e32 v[54:55], v[6:7]
	v_mov_b64_e32 v[52:53], v[4:5]
	v_mov_b64_e32 v[50:51], v[2:3]
	v_mov_b64_e32 v[46:47], v[14:15]
	v_mov_b64_e32 v[44:45], v[12:13]
	v_mov_b64_e32 v[42:43], v[10:11]
	v_mov_b64_e32 v[40:41], v[8:9]
	v_mov_b64_e32 v[38:39], v[6:7]
	v_mov_b64_e32 v[36:37], v[4:5]
	v_mov_b64_e32 v[34:35], v[2:3]
	v_mov_b64_e32 v[30:31], v[14:15]
	v_mov_b64_e32 v[28:29], v[12:13]
	v_mov_b64_e32 v[26:27], v[10:11]
	v_mov_b64_e32 v[24:25], v[8:9]
	v_mov_b64_e32 v[22:23], v[6:7]
	v_mov_b64_e32 v[20:21], v[4:5]
	v_mov_b64_e32 v[18:19], v[2:3]
	.p2alignl 6, 3212836864

; #define WAIT_BAR(N) asm volatile("s_waitcnt vmcnt(" #N ") lgkmcnt(0)\n\ts_barrier":::"memory")
;   #define DMA_K(t,slot) glds16(ksrc+(long)(t)*KVBLK*DM,(unsigned)__builtin_amdgcn_readfirstlane(kdst+(slot)))
;   #define DMA_V(t,slot) do{ glds16(vsrc+(long)(t)*KVBLK*DM,(unsigned)__builtin_amdgcn_readfirstlane(vdst+2*(slot))); glds16(vsrc+64+(long)(t)*KVBLK*DM,(unsigned)__builtin_amdgcn_readfirstlane(vdst+2*(slot)+8192)); }while(0)
;   #define CMASK(P0,P1,t) do{int jb_=(t)-(NT-4); if(jb_>=0)cmask(P0,P1,jb_,qrel,hi);}while(0)
;   #define START(P0,P1) do{ const float rm=rowmax(P0,P1); resc=false; mhat=fadd_s(mhat,rm); \
;     _Pragma("unroll") for(int r=0;r<16;++r){P0[r]=fsub_s(P0[r],mhat);P1[r]=fsub_s(P1[r],mhat);} \
;     _Pragma("unroll") for(int r=0;r<16;++r)P0[r]=__builtin_amdgcn_exp2f(P0[r]); }while(0)
;   #define ROT() do{sl_prev=sl_cur;sl_cur=sl_next;sl_next=(sl_next==(NSLOT-1)*SLOTB)?0:sl_next+SLOTB;}while(0)
;   #define CMASK(P0,P1,t) do{}while(0)
;   #define CMASK(P0,P1,t) do{int jb_=(t)-(NT-4); if(jb_>=0)cmask(P0,P1,jb_,qrel,hi);}while(0)
; template<int THRL,int MODE> __device__ __forceinline__ void attn_unit(int b,int qb,const bf16*Q,const bf16*__restrict__ K,const bf16*__restrict__ V,bf16*O,bf16*O2,char*shm,bf16*CM,float lam,const float*gn){
;     ...
;   f32x16 pA0,pA1,pB0,pB1;
;   int sl_prev=0,sl_cur=0,sl_next=SLOTB;
;     ...
;   DMA_K(2,2*SLOTB);
;   WAIT_BAR(4);
;   qkt(pA0,pA1,Kbase,qr,r32,hi);asm volatile("s_nop 15\n\ts_nop 7":"+v"(pA0),"+v"(pA1));CMASK(pA0,pA1,0);
;   START(pA0,pA1);
;   _Pragma("unroll") for(int r=0;r<16;++r)pA1[r]=__builtin_amdgcn_exp2f(pA1[r]);
;   WAIT_BAR(0);
;   DMA_K(3,0);DMA_V(1,SLOTB);
;   ROT();
;   kload8(kf,kp0+sl_cur);
;   WAIT_BAR(3);
.LBB0_1261:
	v_lshlrev_b32_e32 v2, 1, v36
	v_and_b32_e32 v245, 32, v2
	v_lshlrev_b32_e32 v2, 4, v36
	v_and_b32_e32 v2, 0xc0, v2
	v_lshl_or_b32 v243, v214, 8, v2
	v_add_u32_e32 v2, 0, v245
	v_add3_u32 v249, v2, v242, v243
	v_max3_f32 v2, v20, v21, v4
	v_max3_f32 v36, v22, v23, v5
	s_and_b32 s1, s1, 0x3fffffc0
	v_max3_f32 v2, v2, v6, v7
	v_max3_f32 v36, v36, v26, v27
	s_lshl_b32 s1, s1, 2
	v_max3_f32 v2, v2, v24, v25
	v_max3_f32 v36, v36, v10, v11
	s_add_i32 s57, s1, 0
	v_max3_f32 v2, v2, v8, v9
	v_max3_f32 v36, v36, v30, v31
	s_add_i32 s57, s57, 0x12000
	v_max3_f32 v2, v2, v28, v29
	v_max3_f32 v36, v36, v14, v15
	s_waitcnt vmcnt(0) lgkmcnt(0)
	s_barrier
	s_cmp_lg_u32 0, -1
	v_max3_f32 v2, v2, v12, v13
	v_max3_f32 v36, v36, v34, v35
	s_mov_b32 s16, 1
	v_max3_f32 v2, v2, v32, v33
	v_max3_f32 v36, v36, v18, v19
	s_mov_b32 s1, 0
	v_max3_f32 v2, v2, v16, v17
	v_lshlrev_b32_e32 v250, 4, v214
	v_max_f32_e32 v2, v2, v36
	v_lshl_add_u32 v244, v239, 2, s57
	v_mov_b32_e32 v36, v2
	s_nop 1
	v_permlane32_swap_b32_e32 v2, v36
	v_max_f32_e32 v2, v2, v36
	s_nop 0
	v_add_f32_e32 v246, v3, v2
	s_nop 0
	v_sub_f32_e32 v4, v4, v246
	v_sub_f32_e32 v5, v5, v246
	v_sub_f32_e32 v2, v20, v246
	v_sub_f32_e32 v20, v21, v246
	v_sub_f32_e32 v21, v22, v246
	v_sub_f32_e32 v6, v6, v246
	s_nop 0
	v_exp_f32_e32 v82, v4
	v_exp_f32_e32 v83, v5
	v_lshl_add_u64 v[4:5], v[224:225], 0, s[24:25]
	s_mov_b32 s2, m0
	s_mov_b32 m0, s86
	s_nop 0
	global_load_lds_dwordx4 v[4:5], off
	s_mov_b32 m0, s2
	s_cselect_b32 s2, 0, 0
	s_add_i32 s0, s2, s0
	v_lshl_add_u64 v[4:5], v[226:227], 0, s[20:21]
	s_add_i32 s2, s0, 0xa000
	s_mov_b32 s4, m0
	s_mov_b32 m0, s2
	s_nop 0
	global_load_lds_dwordx4 v[4:5], off
	s_mov_b32 m0, s4
	v_lshl_add_u64 v[4:5], v[226:227], 0, s[26:27]
	s_add_i32 s0, s0, 0xc000
	s_mov_b32 s2, m0
	s_mov_b32 m0, s0
	s_nop 0
	global_load_lds_dwordx4 v[4:5], off
	s_mov_b32 m0, s2
	ds_read_b128 v[206:209], v248 offset:8192
	ds_read_b128 v[202:205], v248 offset:8704
	ds_read_b128 v[198:201], v248 offset:10240
	ds_read_b128 v[194:197], v248 offset:10752
	ds_read_b128 v[190:193], v248 offset:12288
	ds_read_b128 v[186:189], v248 offset:12800
	ds_read_b128 v[182:185], v248 offset:14336
	ds_read_b128 v[178:181], v248 offset:14848
	v_sub_f32_e32 v22, v23, v246
	v_sub_f32_e32 v7, v7, v246
	v_sub_f32_e32 v23, v24, v246
	v_sub_f32_e32 v8, v8, v246
	v_sub_f32_e32 v24, v25, v246
	v_sub_f32_e32 v9, v9, v246
	v_sub_f32_e32 v25, v26, v246
	v_sub_f32_e32 v10, v10, v246
	v_sub_f32_e32 v26, v27, v246
	v_sub_f32_e32 v11, v11, v246
	v_sub_f32_e32 v27, v28, v246
	v_sub_f32_e32 v12, v12, v246
	v_sub_f32_e32 v28, v29, v246
	v_sub_f32_e32 v13, v13, v246
	v_sub_f32_e32 v29, v30, v246
	v_sub_f32_e32 v14, v14, v246
	v_sub_f32_e32 v30, v31, v246
	v_sub_f32_e32 v15, v15, v246
	v_sub_f32_e32 v31, v32, v246
	v_sub_f32_e32 v16, v16, v246
	v_sub_f32_e32 v32, v33, v246
	v_sub_f32_e32 v17, v17, v246
	v_sub_f32_e32 v33, v34, v246
	v_sub_f32_e32 v18, v18, v246
	v_sub_f32_e32 v34, v35, v246
	v_sub_f32_e32 v19, v19, v246
	v_exp_f32_e32 v98, v2
	v_exp_f32_e32 v99, v20
	v_exp_f32_e32 v100, v21
	v_exp_f32_e32 v101, v22
	v_exp_f32_e32 v102, v23
	v_exp_f32_e32 v103, v24
	v_exp_f32_e32 v104, v25
	v_exp_f32_e32 v105, v26
	v_exp_f32_e32 v106, v27
	v_exp_f32_e32 v107, v28
	v_exp_f32_e32 v108, v29
	v_exp_f32_e32 v109, v30
	v_exp_f32_e32 v110, v31
	v_exp_f32_e32 v111, v32
	v_exp_f32_e32 v112, v33
	v_exp_f32_e32 v113, v34
	v_exp_f32_e32 v84, v6
	v_exp_f32_e32 v85, v7
	v_exp_f32_e32 v86, v8
	v_exp_f32_e32 v87, v9
	v_exp_f32_e32 v88, v10
	v_exp_f32_e32 v89, v11
	v_exp_f32_e32 v90, v12
	v_exp_f32_e32 v91, v13
	v_exp_f32_e32 v92, v14
	v_exp_f32_e32 v93, v15
	v_exp_f32_e32 v94, v16
	v_exp_f32_e32 v95, v17
	v_exp_f32_e32 v96, v18
	v_exp_f32_e32 v97, v19
	s_waitcnt vmcnt(3) lgkmcnt(0)
	s_barrier
	s_and_b64 vcc, exec, s[6:7]
	v_cmp_gt_u32_e64 s[6:7], 32, v238
	s_cbranch_vccnz .LBB0_1327
	v_mov_b32_e32 v16, v3
	v_mov_b32_e32 v17, v3
	v_mov_b32_e32 v2, v3
	v_mov_b32_e32 v4, v3
	v_mov_b32_e32 v5, v3
	v_mov_b32_e32 v6, v3
	v_mov_b32_e32 v7, v3
	v_mov_b32_e32 v8, v3
	v_mov_b32_e32 v9, v3
	v_mov_b32_e32 v10, v3
	v_mov_b32_e32 v11, v3
	v_mov_b32_e32 v12, v3
	v_mov_b32_e32 v13, v3
	v_mov_b32_e32 v14, v3
	v_mov_b32_e32 v15, v3
	v_mov_b64_e32 v[80:81], v[16:17]
	v_mov_b64_e32 v[64:65], v[16:17]
	v_mov_b64_e32 v[48:49], v[16:17]
	v_mov_b64_e32 v[32:33], v[16:17]
	s_mov_b32 s8, 0
	s_movk_i32 s1, 0x4000
	s_movk_i32 s16, 0x2000
	v_mov_b32_e32 v251, 0
	s_mov_b32 s2, 6
	s_mov_b64 s[4:5], 0
	v_mov_b64_e32 v[78:79], v[14:15]
	v_mov_b64_e32 v[76:77], v[12:13]
	v_mov_b64_e32 v[74:75], v[10:11]
	v_mov_b64_e32 v[72:73], v[8:9]
	v_mov_b64_e32 v[70:71], v[6:7]
	v_mov_b64_e32 v[68:69], v[4:5]
	v_mov_b64_e32 v[66:67], v[2:3]
	v_mov_b64_e32 v[62:63], v[14:15]
	v_mov_b64_e32 v[60:61], v[12:13]
	v_mov_b64_e32 v[58:59], v[10:11]
	v_mov_b64_e32 v[56:57], v[8:9]
	v_mov_b64_e32 v[54:55], v[6:7]
	v_mov_b64_e32 v[52:53], v[4:5]
	v_mov_b64_e32 v[50:51], v[2:3]
	v_mov_b64_e32 v[46:47], v[14:15]
	v_mov_b64_e32 v[44:45], v[12:13]
	v_mov_b64_e32 v[42:43], v[10:11]
	v_mov_b64_e32 v[40:41], v[8:9]
	v_mov_b64_e32 v[38:39], v[6:7]
	v_mov_b64_e32 v[36:37], v[4:5]
	v_mov_b64_e32 v[34:35], v[2:3]
	v_mov_b64_e32 v[30:31], v[14:15]
	v_mov_b64_e32 v[28:29], v[12:13]
	v_mov_b64_e32 v[26:27], v[10:11]
	v_mov_b64_e32 v[24:25], v[8:9]
	v_mov_b64_e32 v[22:23], v[6:7]
	v_mov_b64_e32 v[20:21], v[4:5]
	v_mov_b64_e32 v[18:19], v[2:3]
	.p2alignl 6, 3212836864

;     __device__ __forceinline__ bool next(int i, Unit& u) const { const int L = i * G + c; if (L >= nM * nN * ng) return false; const int per = nM * nN, r = L % per; u.g = L / per; u.pn = r / nM; u.pm = r % nM; return true; }
; template <class Epi, class Sched, bool ALIGN_EPI = false, bool SP2 = false>
; __device__ __forceinline__ void gemm_phase(PG8_LAS unsigned char* lds, const Gemm g, const Sched& S, const Epi& E) {
;     ...
;         const bool has_next = S.next(ui + 1, nxt);
;         const char* nA = has_next ? (const char*)g.A + (size_t)nxt.g * g.gsA * 2 + (size_t)nxt.pm * tstepA : cA; const char* nB = has_next ? (const char*)g.Bt + (size_t)nxt.g * g.gsB * 2 + (size_t)nxt.pn * tstepB : cB;
;     ...
; #pragma unroll
;         for (int a = 0; a < 2; ++a)
; #pragma unroll
;             for (int b = 0; b < 2; ++b)
; #pragma unroll
;                 for (int m = 0; m < 4; ++m)
; #pragma unroll
;                     for (int n = 0; n < 2; ++n) acc[a][b][m][n] = (f32x4){0.f, 0.f, 0.f, 0.f};
.LBB0_1466:
	s_ashr_i32 s23, s22, 31
	s_lshl_b64 s[24:25], s[22:23], 19
	s_add_u32 s24, s2, s24
	s_addc_u32 s25, s3, s25
	s_and_b64 s[26:27], s[8:9], exec
	s_cselect_b32 s23, s25, s31
	s_cselect_b32 s29, s24, s30
	s_ashr_i32 s21, s20, 31
	s_lshl_b64 s[26:27], s[20:21], 19
	s_add_u32 s26, s33, s26
	s_addc_u32 s27, s38, s27
	s_and_b64 s[36:37], s[8:9], exec
	s_cselect_b32 s21, s27, s35
	s_cselect_b32 s51, s26, s34
	s_add_u32 s30, s30, 0x40080
	s_addc_u32 s31, s31, 0
	s_add_u32 s52, s34, 0x100
	v_mov_b64_e32 v[2:3], 0
	v_mov_b64_e32 v[4:5], 0
	v_mov_b64_e32 v[6:7], 0
	v_mov_b64_e32 v[8:9], 0
	v_mov_b64_e32 v[10:11], 0
	v_mov_b64_e32 v[12:13], 0
	v_mov_b64_e32 v[14:15], 0
	v_mov_b64_e32 v[16:17], 0
	v_mov_b64_e32 v[18:19], 0
	v_mov_b64_e32 v[20:21], 0
	v_mov_b64_e32 v[22:23], 0
	v_mov_b64_e32 v[24:25], 0
	v_mov_b64_e32 v[26:27], 0
	v_mov_b64_e32 v[28:29], 0
	v_mov_b64_e32 v[30:31], 0
	v_mov_b64_e32 v[32:33], 0
	v_mov_b64_e32 v[34:35], 0
	v_mov_b64_e32 v[36:37], 0
	v_mov_b64_e32 v[38:39], 0
	v_mov_b64_e32 v[40:41], 0
	v_mov_b64_e32 v[42:43], 0
	v_mov_b64_e32 v[44:45], 0
	v_mov_b64_e32 v[46:47], 0
	v_mov_b64_e32 v[48:49], 0
	v_mov_b64_e32 v[50:51], 0
	v_mov_b64_e32 v[52:53], 0
	v_mov_b64_e32 v[54:55], 0
	v_mov_b64_e32 v[56:57], 0
	v_mov_b64_e32 v[58:59], 0
	v_mov_b64_e32 v[60:61], 0
	v_mov_b64_e32 v[62:63], 0
	v_mov_b64_e32 v[64:65], 0
	v_mov_b64_e32 v[66:67], 0
	v_mov_b64_e32 v[68:69], 0
	v_mov_b64_e32 v[70:71], 0
	v_mov_b64_e32 v[72:73], 0
	v_mov_b64_e32 v[74:75], 0
	v_mov_b64_e32 v[76:77], 0
	v_mov_b64_e32 v[78:79], 0
	v_mov_b64_e32 v[80:81], 0
	v_mov_b64_e32 v[82:83], 0
	v_mov_b64_e32 v[84:85], 0
	v_mov_b64_e32 v[86:87], 0
	v_mov_b64_e32 v[88:89], 0
	v_mov_b64_e32 v[90:91], 0
	v_mov_b64_e32 v[92:93], 0
	v_mov_b64_e32 v[94:95], 0
	v_mov_b64_e32 v[96:97], 0
	v_mov_b64_e32 v[98:99], 0
	v_mov_b64_e32 v[100:101], 0
	v_mov_b64_e32 v[102:103], 0
	v_mov_b64_e32 v[104:105], 0
	v_mov_b64_e32 v[106:107], 0
	v_mov_b64_e32 v[108:109], 0
	v_mov_b64_e32 v[110:111], 0
	v_mov_b64_e32 v[112:113], 0
	v_mov_b64_e32 v[114:115], 0
	v_mov_b64_e32 v[116:117], 0
	v_mov_b64_e32 v[118:119], 0
	v_mov_b64_e32 v[120:121], 0
	v_mov_b64_e32 v[122:123], 0
	v_mov_b64_e32 v[124:125], 0
	v_mov_b64_e32 v[126:127], 0
	v_mov_b64_e32 v[128:129], 0
	s_addc_u32 s53, s35, 0
	s_mov_b32 s54, -2
	s_waitcnt lgkmcnt(0)
	.p2alignl 6, 3212836864
